# GEMM K-loops: priority raised during the LOAD segments (s_setprio 1 after the post-MFMA barrier, 0 before the pre-MFMA barrier)
# baseline (speedup 1.0000x reference)
.LBB0_253:
	s_add_u32 s26, s0, 0xfffc0080
	s_addc_u32 s27, s1, -1
	s_add_i32 s55, 0, 0x10000
	s_cmp_eq_u32 s54, 12
	s_cselect_b32 s31, s19, s27
	s_cselect_b32 s30, s50, s26
	v_add_u32_e32 v138, s55, v141
	s_cselect_b32 s27, s11, s53
	s_cselect_b32 s26, s51, s52
	s_add_i32 s58, 0, 0x14000
	ds_read_b128 v[144:147], v138
	ds_read_b128 v[158:161], v138 offset:1024
	ds_read_b128 v[162:165], v138 offset:2048
	ds_read_b128 v[166:169], v138 offset:3072
	v_add_u32_e32 v138, s58, v141
	ds_read_b128 v[170:173], v138
	ds_read_b128 v[174:177], v138 offset:1024
	ds_read_b128 v[178:181], v138 offset:2048
	ds_read_b128 v[182:185], v138 offset:3072
	v_lshl_add_u64 v[138:139], s[0:1], 0, v[134:135]
	s_add_i32 m0, s38, 0xc000
	ds_read_b128 v[186:189], v143
	ds_read_b128 v[190:193], v143 offset:1024
	ds_read_b128 v[194:197], v143 offset:2048
	ds_read_b128 v[198:201], v143 offset:3072
	ds_read_b128 v[202:205], v143 offset:4096
	ds_read_b128 v[218:221], v143 offset:5120
	ds_read_b128 v[222:225], v143 offset:6144
	ds_read_b128 v[226:229], v143 offset:7168
	global_load_lds_dwordx4 v[138:139], off
	v_lshl_add_u64 v[138:139], s[0:1], 0, v[136:137]
	s_add_i32 m0, s38, 0xe000
	s_nop 0
	global_load_lds_dwordx4 v[138:139], off
	s_waitcnt vmcnt(8)
	s_waitcnt lgkmcnt(0)
	s_setprio 0
	s_barrier
	s_waitcnt lgkmcnt(0)
	v_mfma_f32_16x16x32_bf16 v[124:127], v[144:147], v[186:189], v[124:127]
	v_mfma_f32_16x16x32_bf16 v[116:119], v[162:165], v[186:189], v[116:119]
	v_mfma_f32_16x16x32_bf16 v[108:111], v[144:147], v[194:197], v[108:111]
	v_mfma_f32_16x16x32_bf16 v[100:103], v[162:165], v[194:197], v[100:103]
	v_mfma_f32_16x16x32_bf16 v[92:95], v[144:147], v[202:205], v[92:95]
	v_mfma_f32_16x16x32_bf16 v[84:87], v[162:165], v[202:205], v[84:87]
	v_mfma_f32_16x16x32_bf16 v[76:79], v[144:147], v[222:225], v[76:79]
	v_mfma_f32_16x16x32_bf16 v[68:71], v[162:165], v[222:225], v[68:71]
	v_mfma_f32_16x16x32_bf16 v[124:127], v[158:161], v[190:193], v[124:127]
	v_mfma_f32_16x16x32_bf16 v[116:119], v[166:169], v[190:193], v[116:119]
	v_mfma_f32_16x16x32_bf16 v[108:111], v[158:161], v[198:201], v[108:111]
	v_mfma_f32_16x16x32_bf16 v[100:103], v[166:169], v[198:201], v[100:103]
	v_mfma_f32_16x16x32_bf16 v[92:95], v[158:161], v[218:221], v[92:95]
	v_mfma_f32_16x16x32_bf16 v[84:87], v[166:169], v[218:221], v[84:87]
	v_mfma_f32_16x16x32_bf16 v[76:79], v[158:161], v[226:229], v[76:79]
	v_mfma_f32_16x16x32_bf16 v[68:71], v[166:169], v[226:229], v[68:71]
	v_mfma_f32_16x16x32_bf16 v[120:123], v[170:173], v[186:189], v[120:123]
	v_mfma_f32_16x16x32_bf16 v[112:115], v[178:181], v[186:189], v[112:115]
	v_mfma_f32_16x16x32_bf16 v[104:107], v[170:173], v[194:197], v[104:107]
	v_mfma_f32_16x16x32_bf16 v[96:99], v[178:181], v[194:197], v[96:99]
	v_mfma_f32_16x16x32_bf16 v[88:91], v[170:173], v[202:205], v[88:91]
	v_mfma_f32_16x16x32_bf16 v[80:83], v[178:181], v[202:205], v[80:83]
	v_mfma_f32_16x16x32_bf16 v[72:75], v[170:173], v[222:225], v[72:75]
	v_mfma_f32_16x16x32_bf16 v[64:67], v[178:181], v[222:225], v[64:67]
	v_mfma_f32_16x16x32_bf16 v[120:123], v[174:177], v[190:193], v[120:123]
	v_mfma_f32_16x16x32_bf16 v[112:115], v[182:185], v[190:193], v[112:115]
	v_mfma_f32_16x16x32_bf16 v[104:107], v[174:177], v[198:201], v[104:107]
	v_mfma_f32_16x16x32_bf16 v[96:99], v[182:185], v[198:201], v[96:99]
	v_mfma_f32_16x16x32_bf16 v[88:91], v[174:177], v[218:221], v[88:91]
	v_mfma_f32_16x16x32_bf16 v[80:83], v[182:185], v[218:221], v[80:83]
	v_mfma_f32_16x16x32_bf16 v[72:75], v[174:177], v[226:229], v[72:75]
	v_mfma_f32_16x16x32_bf16 v[64:67], v[182:185], v[226:229], v[64:67]
	s_barrier
	s_setprio 1
	s_add_i32 s55, s55, s37
	v_lshl_add_u64 v[138:139], s[26:27], 0, v[148:149]
	s_mov_b32 m0, s55
	ds_read_b128 v[186:189], v143 offset:16384
	ds_read_b128 v[190:193], v143 offset:17408
	ds_read_b128 v[194:197], v143 offset:18432
	ds_read_b128 v[198:201], v143 offset:19456
	ds_read_b128 v[202:205], v143 offset:20480
	ds_read_b128 v[218:221], v143 offset:21504
	ds_read_b128 v[222:225], v143 offset:22528
	ds_read_b128 v[226:229], v143 offset:23552
	global_load_lds_dwordx4 v[138:139], off
	s_add_i32 m0, s55, 0x2000
	s_add_u32 s56, s26, 0x40000
	v_lshl_add_u64 v[154:155], s[26:27], 0, v[128:129]
	s_addc_u32 s57, s27, 0
	s_add_i32 s55, s58, s37
	global_load_lds_dwordx4 v[154:155], off
	v_lshl_add_u64 v[156:157], s[56:57], 0, v[148:149]
	s_mov_b32 m0, s55
	v_lshl_add_u64 v[212:213], s[30:31], 0, v[130:131]
	global_load_lds_dwordx4 v[156:157], off
	v_lshl_add_u64 v[156:157], s[56:57], 0, v[128:129]
	s_add_i32 m0, s55, 0x2000
	s_nop 0
	global_load_lds_dwordx4 v[156:157], off
	v_lshl_add_u64 v[156:157], s[30:31], 0, v[132:133]
	s_mov_b32 m0, s38
	s_nop 0
	global_load_lds_dwordx4 v[156:157], off
	s_mov_b32 m0, s39
	s_nop 0
	global_load_lds_dwordx4 v[212:213], off
	s_waitcnt vmcnt(8)
	s_waitcnt lgkmcnt(0)
	s_setprio 0
	s_barrier
	s_waitcnt lgkmcnt(0)
	v_mfma_f32_16x16x32_bf16 v[60:63], v[144:147], v[186:189], v[60:63]
	v_mfma_f32_16x16x32_bf16 v[52:55], v[162:165], v[186:189], v[52:55]
	v_mfma_f32_16x16x32_bf16 v[44:47], v[144:147], v[194:197], v[44:47]
	v_mfma_f32_16x16x32_bf16 v[36:39], v[162:165], v[194:197], v[36:39]
	v_mfma_f32_16x16x32_bf16 v[28:31], v[144:147], v[202:205], v[28:31]
	v_mfma_f32_16x16x32_bf16 v[20:23], v[162:165], v[202:205], v[20:23]
	v_mfma_f32_16x16x32_bf16 v[12:15], v[144:147], v[222:225], v[12:15]
	v_mfma_f32_16x16x32_bf16 v[4:7], v[162:165], v[222:225], v[4:7]
	v_mfma_f32_16x16x32_bf16 v[60:63], v[158:161], v[190:193], v[60:63]
	v_mfma_f32_16x16x32_bf16 v[52:55], v[166:169], v[190:193], v[52:55]
	v_mfma_f32_16x16x32_bf16 v[44:47], v[158:161], v[198:201], v[44:47]
	v_mfma_f32_16x16x32_bf16 v[36:39], v[166:169], v[198:201], v[36:39]
	v_mfma_f32_16x16x32_bf16 v[28:31], v[158:161], v[218:221], v[28:31]
	v_mfma_f32_16x16x32_bf16 v[20:23], v[166:169], v[218:221], v[20:23]
	v_mfma_f32_16x16x32_bf16 v[12:15], v[158:161], v[226:229], v[12:15]
	v_mfma_f32_16x16x32_bf16 v[4:7], v[166:169], v[226:229], v[4:7]
	v_mfma_f32_16x16x32_bf16 v[56:59], v[170:173], v[186:189], v[56:59]
	v_mfma_f32_16x16x32_bf16 v[48:51], v[178:181], v[186:189], v[48:51]
	v_mfma_f32_16x16x32_bf16 v[40:43], v[170:173], v[194:197], v[40:43]
	v_mfma_f32_16x16x32_bf16 v[32:35], v[178:181], v[194:197], v[32:35]
	v_mfma_f32_16x16x32_bf16 v[24:27], v[170:173], v[202:205], v[24:27]
	v_mfma_f32_16x16x32_bf16 v[16:19], v[178:181], v[202:205], v[16:19]
	v_mfma_f32_16x16x32_bf16 v[8:11], v[170:173], v[222:225], v[8:11]
	v_mfma_f32_16x16x32_bf16 v[0:3], v[178:181], v[222:225], v[0:3]
	v_mfma_f32_16x16x32_bf16 v[56:59], v[174:177], v[190:193], v[56:59]
	v_mfma_f32_16x16x32_bf16 v[48:51], v[182:185], v[190:193], v[48:51]
	v_mfma_f32_16x16x32_bf16 v[40:43], v[174:177], v[198:201], v[40:43]
	v_mfma_f32_16x16x32_bf16 v[32:35], v[182:185], v[198:201], v[32:35]
	v_mfma_f32_16x16x32_bf16 v[24:27], v[174:177], v[218:221], v[24:27]
	v_mfma_f32_16x16x32_bf16 v[16:19], v[182:185], v[218:221], v[16:19]
	v_mfma_f32_16x16x32_bf16 v[8:11], v[174:177], v[226:229], v[8:11]
	v_mfma_f32_16x16x32_bf16 v[0:3], v[182:185], v[226:229], v[0:3]
	s_barrier
	s_setprio 1
	s_add_i32 s55, 0, 0x18000
	v_add_u32_e32 v140, s55, v141
	s_add_i32 s56, 0, 0x1c000
	ds_read_b128 v[144:147], v140
	ds_read_b128 v[158:161], v140 offset:1024
	ds_read_b128 v[162:165], v140 offset:2048
	ds_read_b128 v[166:169], v140 offset:3072
	v_add_u32_e32 v140, s56, v141
	ds_read_b128 v[170:173], v140
	ds_read_b128 v[174:177], v140 offset:1024
	ds_read_b128 v[178:181], v140 offset:2048
	ds_read_b128 v[182:185], v140 offset:3072
	s_add_u32 s30, s30, 0x40000
	s_addc_u32 s31, s31, 0
	s_mov_b32 m0, s40
	v_lshl_add_u64 v[214:215], s[30:31], 0, v[132:133]
	ds_read_b128 v[186:189], v143 offset:32768
	ds_read_b128 v[190:193], v143 offset:33792
	ds_read_b128 v[194:197], v143 offset:34816
	ds_read_b128 v[198:201], v143 offset:35840
	ds_read_b128 v[202:205], v143 offset:36864
	ds_read_b128 v[218:221], v143 offset:37888
	ds_read_b128 v[222:225], v143 offset:38912
	ds_read_b128 v[226:229], v143 offset:39936
	global_load_lds_dwordx4 v[214:215], off
	v_lshl_add_u64 v[214:215], s[30:31], 0, v[130:131]
	s_mov_b32 m0, s41
	s_nop 0
	global_load_lds_dwordx4 v[214:215], off
	s_waitcnt vmcnt(8)
	s_waitcnt lgkmcnt(0)
	s_setprio 0
	s_barrier
	s_waitcnt lgkmcnt(0)
	v_mfma_f32_16x16x32_bf16 v[124:127], v[144:147], v[186:189], v[124:127]
	v_mfma_f32_16x16x32_bf16 v[116:119], v[162:165], v[186:189], v[116:119]
	v_mfma_f32_16x16x32_bf16 v[108:111], v[144:147], v[194:197], v[108:111]
	v_mfma_f32_16x16x32_bf16 v[100:103], v[162:165], v[194:197], v[100:103]
	v_mfma_f32_16x16x32_bf16 v[92:95], v[144:147], v[202:205], v[92:95]
	v_mfma_f32_16x16x32_bf16 v[84:87], v[162:165], v[202:205], v[84:87]
	v_mfma_f32_16x16x32_bf16 v[76:79], v[144:147], v[222:225], v[76:79]
	v_mfma_f32_16x16x32_bf16 v[68:71], v[162:165], v[222:225], v[68:71]
	v_mfma_f32_16x16x32_bf16 v[124:127], v[158:161], v[190:193], v[124:127]
	v_mfma_f32_16x16x32_bf16 v[116:119], v[166:169], v[190:193], v[116:119]
	v_mfma_f32_16x16x32_bf16 v[108:111], v[158:161], v[198:201], v[108:111]
	v_mfma_f32_16x16x32_bf16 v[100:103], v[166:169], v[198:201], v[100:103]
	v_mfma_f32_16x16x32_bf16 v[92:95], v[158:161], v[218:221], v[92:95]
	v_mfma_f32_16x16x32_bf16 v[84:87], v[166:169], v[218:221], v[84:87]
	v_mfma_f32_16x16x32_bf16 v[76:79], v[158:161], v[226:229], v[76:79]
	v_mfma_f32_16x16x32_bf16 v[68:71], v[166:169], v[226:229], v[68:71]
	v_mfma_f32_16x16x32_bf16 v[120:123], v[170:173], v[186:189], v[120:123]
	v_mfma_f32_16x16x32_bf16 v[112:115], v[178:181], v[186:189], v[112:115]
	v_mfma_f32_16x16x32_bf16 v[104:107], v[170:173], v[194:197], v[104:107]
	v_mfma_f32_16x16x32_bf16 v[96:99], v[178:181], v[194:197], v[96:99]
	v_mfma_f32_16x16x32_bf16 v[88:91], v[170:173], v[202:205], v[88:91]
	v_mfma_f32_16x16x32_bf16 v[80:83], v[178:181], v[202:205], v[80:83]
	v_mfma_f32_16x16x32_bf16 v[72:75], v[170:173], v[222:225], v[72:75]
	v_mfma_f32_16x16x32_bf16 v[64:67], v[178:181], v[222:225], v[64:67]
	v_mfma_f32_16x16x32_bf16 v[120:123], v[174:177], v[190:193], v[120:123]
	v_mfma_f32_16x16x32_bf16 v[112:115], v[182:185], v[190:193], v[112:115]
	v_mfma_f32_16x16x32_bf16 v[104:107], v[174:177], v[198:201], v[104:107]
	v_mfma_f32_16x16x32_bf16 v[96:99], v[182:185], v[198:201], v[96:99]
	v_mfma_f32_16x16x32_bf16 v[88:91], v[174:177], v[218:221], v[88:91]
	v_mfma_f32_16x16x32_bf16 v[80:83], v[182:185], v[218:221], v[80:83]
	v_mfma_f32_16x16x32_bf16 v[72:75], v[174:177], v[226:229], v[72:75]
	v_mfma_f32_16x16x32_bf16 v[64:67], v[182:185], v[226:229], v[64:67]
	s_barrier
	s_setprio 1
	s_add_i32 s30, s55, s37
	v_lshl_add_u64 v[138:139], v[138:139], 0, s[28:29]
	s_mov_b32 m0, s30
	ds_read_b128 v[186:189], v143 offset:49152
	ds_read_b128 v[190:193], v143 offset:50176
	ds_read_b128 v[194:197], v143 offset:51200
	ds_read_b128 v[198:201], v143 offset:52224
	ds_read_b128 v[202:205], v143 offset:53248
	ds_read_b128 v[218:221], v143 offset:54272
	ds_read_b128 v[222:225], v143 offset:55296
	ds_read_b128 v[226:229], v143 offset:56320
	global_load_lds_dwordx4 v[138:139], off
	s_add_i32 m0, s30, 0x2000
	s_add_u32 s26, s26, 0x40080
	v_lshl_add_u64 v[138:139], v[154:155], 0, s[28:29]
	s_addc_u32 s27, s27, 0
	s_add_i32 s30, s56, s37
	global_load_lds_dwordx4 v[138:139], off
	v_lshl_add_u64 v[138:139], s[26:27], 0, v[148:149]
	s_mov_b32 m0, s30
	s_nop 0
	global_load_lds_dwordx4 v[138:139], off
	v_lshl_add_u64 v[138:139], s[26:27], 0, v[128:129]
	s_add_i32 m0, s30, 0x2000
	s_nop 0
	global_load_lds_dwordx4 v[138:139], off
	v_lshl_add_u64 v[138:139], v[156:157], 0, s[28:29]
	s_mov_b32 m0, s46
	s_nop 0
	global_load_lds_dwordx4 v[138:139], off
	v_lshl_add_u64 v[138:139], v[212:213], 0, s[28:29]
	s_mov_b32 m0, s47
	s_nop 0
	global_load_lds_dwordx4 v[138:139], off
	s_waitcnt vmcnt(8)
	s_waitcnt lgkmcnt(0)
	s_setprio 0
	s_barrier
	s_waitcnt lgkmcnt(0)
	v_mfma_f32_16x16x32_bf16 v[60:63], v[144:147], v[186:189], v[60:63]
	v_mfma_f32_16x16x32_bf16 v[52:55], v[162:165], v[186:189], v[52:55]
	v_mfma_f32_16x16x32_bf16 v[44:47], v[144:147], v[194:197], v[44:47]
	v_mfma_f32_16x16x32_bf16 v[36:39], v[162:165], v[194:197], v[36:39]
	v_mfma_f32_16x16x32_bf16 v[28:31], v[144:147], v[202:205], v[28:31]
	v_mfma_f32_16x16x32_bf16 v[20:23], v[162:165], v[202:205], v[20:23]
	v_mfma_f32_16x16x32_bf16 v[12:15], v[144:147], v[222:225], v[12:15]
	v_mfma_f32_16x16x32_bf16 v[4:7], v[162:165], v[222:225], v[4:7]
	v_mfma_f32_16x16x32_bf16 v[60:63], v[158:161], v[190:193], v[60:63]
	v_mfma_f32_16x16x32_bf16 v[52:55], v[166:169], v[190:193], v[52:55]
	v_mfma_f32_16x16x32_bf16 v[44:47], v[158:161], v[198:201], v[44:47]
	v_mfma_f32_16x16x32_bf16 v[36:39], v[166:169], v[198:201], v[36:39]
	v_mfma_f32_16x16x32_bf16 v[28:31], v[158:161], v[218:221], v[28:31]
	v_mfma_f32_16x16x32_bf16 v[20:23], v[166:169], v[218:221], v[20:23]
	v_mfma_f32_16x16x32_bf16 v[12:15], v[158:161], v[226:229], v[12:15]
	v_mfma_f32_16x16x32_bf16 v[4:7], v[166:169], v[226:229], v[4:7]
	v_mfma_f32_16x16x32_bf16 v[56:59], v[170:173], v[186:189], v[56:59]
	v_mfma_f32_16x16x32_bf16 v[48:51], v[178:181], v[186:189], v[48:51]
	v_mfma_f32_16x16x32_bf16 v[40:43], v[170:173], v[194:197], v[40:43]
	v_mfma_f32_16x16x32_bf16 v[32:35], v[178:181], v[194:197], v[32:35]
	v_mfma_f32_16x16x32_bf16 v[24:27], v[170:173], v[202:205], v[24:27]
	v_mfma_f32_16x16x32_bf16 v[16:19], v[178:181], v[202:205], v[16:19]
	v_mfma_f32_16x16x32_bf16 v[8:11], v[170:173], v[222:225], v[8:11]
	v_mfma_f32_16x16x32_bf16 v[0:3], v[178:181], v[222:225], v[0:3]
	v_mfma_f32_16x16x32_bf16 v[56:59], v[174:177], v[190:193], v[56:59]
	v_mfma_f32_16x16x32_bf16 v[48:51], v[182:185], v[190:193], v[48:51]
	v_mfma_f32_16x16x32_bf16 v[40:43], v[174:177], v[198:201], v[40:43]
	v_mfma_f32_16x16x32_bf16 v[32:35], v[182:185], v[198:201], v[32:35]
	v_mfma_f32_16x16x32_bf16 v[24:27], v[174:177], v[218:221], v[24:27]
	v_mfma_f32_16x16x32_bf16 v[16:19], v[182:185], v[218:221], v[16:19]
	v_mfma_f32_16x16x32_bf16 v[8:11], v[174:177], v[226:229], v[8:11]
	v_mfma_f32_16x16x32_bf16 v[0:3], v[182:185], v[226:229], v[0:3]
	s_barrier
	s_setprio 1
	s_add_i32 s54, s54, 2
	s_add_u32 s0, s0, 0x100
	s_addc_u32 s1, s1, 0
	s_add_u32 s52, s52, 0x100
	s_addc_u32 s53, s53, 0
	s_cmp_gt_u32 s54, 13
	s_cbranch_scc0 .LBB0_253
	s_setprio 0
	s_and_b64 vcc, exec, s[8:9]
	s_cbranch_vccz .LBB0_256
	s_barrier

.LBB0_360:
	s_add_u32 s0, s4, 0x100
	s_addc_u32 s1, s5, 0
	s_add_i32 s45, 0, 0x10000
	s_cmp_eq_u32 s44, 40
	s_cselect_b32 s9, s39, s1
	s_cselect_b32 s8, s38, s0
	v_add_u32_e32 v146, s45, v168
	s_cselect_b32 s3, s41, s43
	s_cselect_b32 s2, s40, s42
	s_add_i32 s62, 0, 0x14000
	ds_read_b128 v[128:131], v146
	ds_read_b128 v[132:135], v146 offset:1024
	ds_read_b128 v[158:161], v146 offset:2048
	ds_read_b128 v[162:165], v146 offset:3072
	v_add_u32_e32 v146, s62, v168
	ds_read_b128 v[170:173], v146
	ds_read_b128 v[174:177], v146 offset:1024
	ds_read_b128 v[178:181], v146 offset:2048
	ds_read_b128 v[182:185], v146 offset:3072
	v_lshl_add_u64 v[146:147], s[4:5], 0, v[142:143]
	s_add_i32 m0, s50, 0xc000
	ds_read_b128 v[186:189], v169
	ds_read_b128 v[190:193], v169 offset:1024
	ds_read_b128 v[194:197], v169 offset:2048
	ds_read_b128 v[198:201], v169 offset:3072
	ds_read_b128 v[202:205], v169 offset:4096
	ds_read_b128 v[218:221], v169 offset:5120
	ds_read_b128 v[222:225], v169 offset:6144
	ds_read_b128 v[226:229], v169 offset:7168
	global_load_lds_dwordx4 v[146:147], off
	v_lshl_add_u64 v[146:147], s[4:5], 0, v[144:145]
	s_add_i32 m0, s50, 0xe000
	s_nop 0
	global_load_lds_dwordx4 v[146:147], off
	s_waitcnt vmcnt(8)
	s_waitcnt lgkmcnt(0)
	s_setprio 0
	s_barrier
	s_waitcnt lgkmcnt(0)
	v_mfma_f32_16x16x32_bf16 v[124:127], v[128:131], v[186:189], v[124:127]
	v_mfma_f32_16x16x32_bf16 v[120:123], v[158:161], v[186:189], v[120:123]
	v_mfma_f32_16x16x32_bf16 v[108:111], v[128:131], v[194:197], v[108:111]
	v_mfma_f32_16x16x32_bf16 v[104:107], v[158:161], v[194:197], v[104:107]
	v_mfma_f32_16x16x32_bf16 v[92:95], v[128:131], v[202:205], v[92:95]
	v_mfma_f32_16x16x32_bf16 v[88:91], v[158:161], v[202:205], v[88:91]
	v_mfma_f32_16x16x32_bf16 v[76:79], v[128:131], v[222:225], v[76:79]
	v_mfma_f32_16x16x32_bf16 v[72:75], v[158:161], v[222:225], v[72:75]
	v_mfma_f32_16x16x32_bf16 v[124:127], v[132:135], v[190:193], v[124:127]
	v_mfma_f32_16x16x32_bf16 v[120:123], v[162:165], v[190:193], v[120:123]
	v_mfma_f32_16x16x32_bf16 v[108:111], v[132:135], v[198:201], v[108:111]
	v_mfma_f32_16x16x32_bf16 v[104:107], v[162:165], v[198:201], v[104:107]
	v_mfma_f32_16x16x32_bf16 v[92:95], v[132:135], v[218:221], v[92:95]
	v_mfma_f32_16x16x32_bf16 v[88:91], v[162:165], v[218:221], v[88:91]
	v_mfma_f32_16x16x32_bf16 v[76:79], v[132:135], v[226:229], v[76:79]
	v_mfma_f32_16x16x32_bf16 v[72:75], v[162:165], v[226:229], v[72:75]
	v_mfma_f32_16x16x32_bf16 v[116:119], v[170:173], v[186:189], v[116:119]
	v_mfma_f32_16x16x32_bf16 v[112:115], v[178:181], v[186:189], v[112:115]
	v_mfma_f32_16x16x32_bf16 v[100:103], v[170:173], v[194:197], v[100:103]
	v_mfma_f32_16x16x32_bf16 v[96:99], v[178:181], v[194:197], v[96:99]
	v_mfma_f32_16x16x32_bf16 v[84:87], v[170:173], v[202:205], v[84:87]
	v_mfma_f32_16x16x32_bf16 v[80:83], v[178:181], v[202:205], v[80:83]
	v_mfma_f32_16x16x32_bf16 v[68:71], v[170:173], v[222:225], v[68:71]
	v_mfma_f32_16x16x32_bf16 v[64:67], v[178:181], v[222:225], v[64:67]
	v_mfma_f32_16x16x32_bf16 v[116:119], v[174:177], v[190:193], v[116:119]
	v_mfma_f32_16x16x32_bf16 v[112:115], v[182:185], v[190:193], v[112:115]
	v_mfma_f32_16x16x32_bf16 v[100:103], v[174:177], v[198:201], v[100:103]
	v_mfma_f32_16x16x32_bf16 v[96:99], v[182:185], v[198:201], v[96:99]
	v_mfma_f32_16x16x32_bf16 v[84:87], v[174:177], v[218:221], v[84:87]
	v_mfma_f32_16x16x32_bf16 v[80:83], v[182:185], v[218:221], v[80:83]
	v_mfma_f32_16x16x32_bf16 v[68:71], v[174:177], v[226:229], v[68:71]
	v_mfma_f32_16x16x32_bf16 v[64:67], v[182:185], v[226:229], v[64:67]
	s_barrier
	s_setprio 1
	s_add_i32 s4, s45, s49
	v_lshl_add_u64 v[146:147], s[2:3], 0, v[148:149]
	s_mov_b32 m0, s4
	ds_read_b128 v[186:189], v169 offset:16384
	ds_read_b128 v[190:193], v169 offset:17408
	ds_read_b128 v[194:197], v169 offset:18432
	ds_read_b128 v[198:201], v169 offset:19456
	ds_read_b128 v[202:205], v169 offset:20480
	ds_read_b128 v[218:221], v169 offset:21504
	ds_read_b128 v[222:225], v169 offset:22528
	ds_read_b128 v[226:229], v169 offset:23552
	global_load_lds_dwordx4 v[146:147], off
	s_add_i32 m0, s4, 0x2000
	s_add_u32 s4, s2, 0xb0000
	v_lshl_add_u64 v[154:155], s[2:3], 0, v[136:137]
	s_addc_u32 s5, s3, 0
	s_add_i32 s45, s62, s49
	global_load_lds_dwordx4 v[154:155], off
	v_lshl_add_u64 v[156:157], s[4:5], 0, v[148:149]
	s_mov_b32 m0, s45
	v_lshl_add_u64 v[166:167], s[8:9], 0, v[138:139]
	global_load_lds_dwordx4 v[156:157], off
	v_lshl_add_u64 v[156:157], s[4:5], 0, v[136:137]
	s_add_i32 m0, s45, 0x2000
	s_nop 0
	global_load_lds_dwordx4 v[156:157], off
	v_lshl_add_u64 v[156:157], s[8:9], 0, v[140:141]
	s_mov_b32 m0, s50
	s_nop 0
	global_load_lds_dwordx4 v[156:157], off
	s_mov_b32 m0, s51
	s_nop 0
	global_load_lds_dwordx4 v[166:167], off
	s_waitcnt vmcnt(8)
	s_waitcnt lgkmcnt(0)
	s_setprio 0
	s_barrier
	s_waitcnt lgkmcnt(0)
	v_mfma_f32_16x16x32_bf16 v[60:63], v[128:131], v[186:189], v[60:63]
	v_mfma_f32_16x16x32_bf16 v[56:59], v[158:161], v[186:189], v[56:59]
	v_mfma_f32_16x16x32_bf16 v[44:47], v[128:131], v[194:197], v[44:47]
	v_mfma_f32_16x16x32_bf16 v[40:43], v[158:161], v[194:197], v[40:43]
	v_mfma_f32_16x16x32_bf16 v[28:31], v[128:131], v[202:205], v[28:31]
	v_mfma_f32_16x16x32_bf16 v[24:27], v[158:161], v[202:205], v[24:27]
	v_mfma_f32_16x16x32_bf16 v[12:15], v[128:131], v[222:225], v[12:15]
	v_mfma_f32_16x16x32_bf16 v[8:11], v[158:161], v[222:225], v[8:11]
	v_mfma_f32_16x16x32_bf16 v[60:63], v[132:135], v[190:193], v[60:63]
	v_mfma_f32_16x16x32_bf16 v[56:59], v[162:165], v[190:193], v[56:59]
	v_mfma_f32_16x16x32_bf16 v[44:47], v[132:135], v[198:201], v[44:47]
	v_mfma_f32_16x16x32_bf16 v[40:43], v[162:165], v[198:201], v[40:43]
	v_mfma_f32_16x16x32_bf16 v[28:31], v[132:135], v[218:221], v[28:31]
	v_mfma_f32_16x16x32_bf16 v[24:27], v[162:165], v[218:221], v[24:27]
	v_mfma_f32_16x16x32_bf16 v[12:15], v[132:135], v[226:229], v[12:15]
	v_mfma_f32_16x16x32_bf16 v[8:11], v[162:165], v[226:229], v[8:11]
	v_mfma_f32_16x16x32_bf16 v[52:55], v[170:173], v[186:189], v[52:55]
	v_mfma_f32_16x16x32_bf16 v[48:51], v[178:181], v[186:189], v[48:51]
	v_mfma_f32_16x16x32_bf16 v[36:39], v[170:173], v[194:197], v[36:39]
	v_mfma_f32_16x16x32_bf16 v[32:35], v[178:181], v[194:197], v[32:35]
	v_mfma_f32_16x16x32_bf16 v[20:23], v[170:173], v[202:205], v[20:23]
	v_mfma_f32_16x16x32_bf16 v[16:19], v[178:181], v[202:205], v[16:19]
	v_mfma_f32_16x16x32_bf16 v[4:7], v[170:173], v[222:225], v[4:7]
	v_mfma_f32_16x16x32_bf16 v[0:3], v[178:181], v[222:225], v[0:3]
	v_mfma_f32_16x16x32_bf16 v[52:55], v[174:177], v[190:193], v[52:55]
	v_mfma_f32_16x16x32_bf16 v[48:51], v[182:185], v[190:193], v[48:51]
	v_mfma_f32_16x16x32_bf16 v[36:39], v[174:177], v[198:201], v[36:39]
	v_mfma_f32_16x16x32_bf16 v[32:35], v[182:185], v[198:201], v[32:35]
	v_mfma_f32_16x16x32_bf16 v[20:23], v[174:177], v[218:221], v[20:23]
	v_mfma_f32_16x16x32_bf16 v[16:19], v[182:185], v[218:221], v[16:19]
	v_mfma_f32_16x16x32_bf16 v[4:7], v[174:177], v[226:229], v[4:7]
	v_mfma_f32_16x16x32_bf16 v[0:3], v[182:185], v[226:229], v[0:3]
	s_barrier
	s_setprio 1
	s_add_i32 s45, 0, 0x18000
	v_add_u32_e32 v150, s45, v168
	s_add_i32 s62, 0, 0x1c000
	ds_read_b128 v[128:131], v150
	ds_read_b128 v[132:135], v150 offset:1024
	ds_read_b128 v[158:161], v150 offset:2048
	ds_read_b128 v[162:165], v150 offset:3072
	v_add_u32_e32 v150, s62, v168
	ds_read_b128 v[170:173], v150
	ds_read_b128 v[174:177], v150 offset:1024
	ds_read_b128 v[178:181], v150 offset:2048
	ds_read_b128 v[182:185], v150 offset:3072
	s_add_u32 s4, s8, 0xb0000
	s_addc_u32 s5, s9, 0
	s_mov_b32 m0, s52
	v_lshl_add_u64 v[212:213], s[4:5], 0, v[140:141]
	ds_read_b128 v[186:189], v169 offset:32768
	ds_read_b128 v[190:193], v169 offset:33792
	ds_read_b128 v[194:197], v169 offset:34816
	ds_read_b128 v[198:201], v169 offset:35840
	ds_read_b128 v[202:205], v169 offset:36864
	ds_read_b128 v[218:221], v169 offset:37888
	ds_read_b128 v[222:225], v169 offset:38912
	ds_read_b128 v[226:229], v169 offset:39936
	global_load_lds_dwordx4 v[212:213], off
	v_lshl_add_u64 v[212:213], s[4:5], 0, v[138:139]
	s_mov_b32 m0, s53
	s_nop 0
	global_load_lds_dwordx4 v[212:213], off
	s_waitcnt vmcnt(8)
	s_waitcnt lgkmcnt(0)
	s_setprio 0
	s_barrier
	s_waitcnt lgkmcnt(0)
	v_mfma_f32_16x16x32_bf16 v[124:127], v[128:131], v[186:189], v[124:127]
	v_mfma_f32_16x16x32_bf16 v[120:123], v[158:161], v[186:189], v[120:123]
	v_mfma_f32_16x16x32_bf16 v[108:111], v[128:131], v[194:197], v[108:111]
	v_mfma_f32_16x16x32_bf16 v[104:107], v[158:161], v[194:197], v[104:107]
	v_mfma_f32_16x16x32_bf16 v[92:95], v[128:131], v[202:205], v[92:95]
	v_mfma_f32_16x16x32_bf16 v[88:91], v[158:161], v[202:205], v[88:91]
	v_mfma_f32_16x16x32_bf16 v[76:79], v[128:131], v[222:225], v[76:79]
	v_mfma_f32_16x16x32_bf16 v[72:75], v[158:161], v[222:225], v[72:75]
	v_mfma_f32_16x16x32_bf16 v[124:127], v[132:135], v[190:193], v[124:127]
	v_mfma_f32_16x16x32_bf16 v[120:123], v[162:165], v[190:193], v[120:123]
	v_mfma_f32_16x16x32_bf16 v[108:111], v[132:135], v[198:201], v[108:111]
	v_mfma_f32_16x16x32_bf16 v[104:107], v[162:165], v[198:201], v[104:107]
	v_mfma_f32_16x16x32_bf16 v[92:95], v[132:135], v[218:221], v[92:95]
	v_mfma_f32_16x16x32_bf16 v[88:91], v[162:165], v[218:221], v[88:91]
	v_mfma_f32_16x16x32_bf16 v[76:79], v[132:135], v[226:229], v[76:79]
	v_mfma_f32_16x16x32_bf16 v[72:75], v[162:165], v[226:229], v[72:75]
	v_mfma_f32_16x16x32_bf16 v[116:119], v[170:173], v[186:189], v[116:119]
	v_mfma_f32_16x16x32_bf16 v[112:115], v[178:181], v[186:189], v[112:115]
	v_mfma_f32_16x16x32_bf16 v[100:103], v[170:173], v[194:197], v[100:103]
	v_mfma_f32_16x16x32_bf16 v[96:99], v[178:181], v[194:197], v[96:99]
	v_mfma_f32_16x16x32_bf16 v[84:87], v[170:173], v[202:205], v[84:87]
	v_mfma_f32_16x16x32_bf16 v[80:83], v[178:181], v[202:205], v[80:83]
	v_mfma_f32_16x16x32_bf16 v[68:71], v[170:173], v[222:225], v[68:71]
	v_mfma_f32_16x16x32_bf16 v[64:67], v[178:181], v[222:225], v[64:67]
	v_mfma_f32_16x16x32_bf16 v[116:119], v[174:177], v[190:193], v[116:119]
	v_mfma_f32_16x16x32_bf16 v[112:115], v[182:185], v[190:193], v[112:115]
	v_mfma_f32_16x16x32_bf16 v[100:103], v[174:177], v[198:201], v[100:103]
	v_mfma_f32_16x16x32_bf16 v[96:99], v[182:185], v[198:201], v[96:99]
	v_mfma_f32_16x16x32_bf16 v[84:87], v[174:177], v[218:221], v[84:87]
	v_mfma_f32_16x16x32_bf16 v[80:83], v[182:185], v[218:221], v[80:83]
	v_mfma_f32_16x16x32_bf16 v[68:71], v[174:177], v[226:229], v[68:71]
	v_mfma_f32_16x16x32_bf16 v[64:67], v[182:185], v[226:229], v[64:67]
	s_barrier
	s_setprio 1
	s_add_i32 s4, s45, s49
	v_lshl_add_u64 v[146:147], v[146:147], 0, s[28:29]
	s_mov_b32 m0, s4
	ds_read_b128 v[186:189], v169 offset:49152
	ds_read_b128 v[190:193], v169 offset:50176
	ds_read_b128 v[194:197], v169 offset:51200
	ds_read_b128 v[198:201], v169 offset:52224
	ds_read_b128 v[202:205], v169 offset:53248
	ds_read_b128 v[218:221], v169 offset:54272
	ds_read_b128 v[222:225], v169 offset:55296
	ds_read_b128 v[226:229], v169 offset:56320
	global_load_lds_dwordx4 v[146:147], off
	s_add_i32 m0, s4, 0x2000
	s_add_u32 s2, s2, 0xb0080
	v_lshl_add_u64 v[146:147], v[154:155], 0, s[28:29]
	s_addc_u32 s3, s3, 0
	s_add_i32 s4, s62, s49
	global_load_lds_dwordx4 v[146:147], off
	v_lshl_add_u64 v[146:147], s[2:3], 0, v[148:149]
	s_mov_b32 m0, s4
	s_nop 0
	global_load_lds_dwordx4 v[146:147], off
	v_lshl_add_u64 v[146:147], s[2:3], 0, v[136:137]
	s_add_i32 m0, s4, 0x2000
	s_nop 0
	global_load_lds_dwordx4 v[146:147], off
	v_lshl_add_u64 v[146:147], v[156:157], 0, s[28:29]
	s_mov_b32 m0, s57
	s_nop 0
	global_load_lds_dwordx4 v[146:147], off
	v_lshl_add_u64 v[146:147], v[166:167], 0, s[28:29]
	s_mov_b32 m0, s58
	s_nop 0
	global_load_lds_dwordx4 v[146:147], off
	s_waitcnt vmcnt(8)
	s_waitcnt lgkmcnt(0)
	s_setprio 0
	s_barrier
	s_waitcnt lgkmcnt(0)
	v_mfma_f32_16x16x32_bf16 v[60:63], v[128:131], v[186:189], v[60:63]
	v_mfma_f32_16x16x32_bf16 v[56:59], v[158:161], v[186:189], v[56:59]
	v_mfma_f32_16x16x32_bf16 v[44:47], v[128:131], v[194:197], v[44:47]
	v_mfma_f32_16x16x32_bf16 v[40:43], v[158:161], v[194:197], v[40:43]
	v_mfma_f32_16x16x32_bf16 v[28:31], v[128:131], v[202:205], v[28:31]
	v_mfma_f32_16x16x32_bf16 v[24:27], v[158:161], v[202:205], v[24:27]
	v_mfma_f32_16x16x32_bf16 v[12:15], v[128:131], v[222:225], v[12:15]
	v_mfma_f32_16x16x32_bf16 v[8:11], v[158:161], v[222:225], v[8:11]
	v_mfma_f32_16x16x32_bf16 v[60:63], v[132:135], v[190:193], v[60:63]
	v_mfma_f32_16x16x32_bf16 v[56:59], v[162:165], v[190:193], v[56:59]
	v_mfma_f32_16x16x32_bf16 v[44:47], v[132:135], v[198:201], v[44:47]
	v_mfma_f32_16x16x32_bf16 v[40:43], v[162:165], v[198:201], v[40:43]
	v_mfma_f32_16x16x32_bf16 v[28:31], v[132:135], v[218:221], v[28:31]
	v_mfma_f32_16x16x32_bf16 v[24:27], v[162:165], v[218:221], v[24:27]
	v_mfma_f32_16x16x32_bf16 v[12:15], v[132:135], v[226:229], v[12:15]
	v_mfma_f32_16x16x32_bf16 v[8:11], v[162:165], v[226:229], v[8:11]
	v_mfma_f32_16x16x32_bf16 v[52:55], v[170:173], v[186:189], v[52:55]
	v_mfma_f32_16x16x32_bf16 v[48:51], v[178:181], v[186:189], v[48:51]
	v_mfma_f32_16x16x32_bf16 v[36:39], v[170:173], v[194:197], v[36:39]
	v_mfma_f32_16x16x32_bf16 v[32:35], v[178:181], v[194:197], v[32:35]
	v_mfma_f32_16x16x32_bf16 v[20:23], v[170:173], v[202:205], v[20:23]
	v_mfma_f32_16x16x32_bf16 v[16:19], v[178:181], v[202:205], v[16:19]
	v_mfma_f32_16x16x32_bf16 v[4:7], v[170:173], v[222:225], v[4:7]
	v_mfma_f32_16x16x32_bf16 v[0:3], v[178:181], v[222:225], v[0:3]
	v_mfma_f32_16x16x32_bf16 v[52:55], v[174:177], v[190:193], v[52:55]
	v_mfma_f32_16x16x32_bf16 v[48:51], v[182:185], v[190:193], v[48:51]
	v_mfma_f32_16x16x32_bf16 v[36:39], v[174:177], v[198:201], v[36:39]
	v_mfma_f32_16x16x32_bf16 v[32:35], v[182:185], v[198:201], v[32:35]
	v_mfma_f32_16x16x32_bf16 v[20:23], v[174:177], v[218:221], v[20:23]
	v_mfma_f32_16x16x32_bf16 v[16:19], v[182:185], v[218:221], v[16:19]
	v_mfma_f32_16x16x32_bf16 v[4:7], v[174:177], v[226:229], v[4:7]
	v_mfma_f32_16x16x32_bf16 v[0:3], v[182:185], v[226:229], v[0:3]
	s_barrier
	s_setprio 1
	s_add_i32 s44, s44, 2
	s_add_u32 s42, s42, 0x100
	s_addc_u32 s43, s43, 0
	s_cmp_gt_u32 s44, 41
	s_mov_b64 s[4:5], s[0:1]
	s_cbranch_scc0 .LBB0_360
	s_setprio 0
	s_and_b64 vcc, exec, s[30:31]
	s_cbranch_vccz .LBB0_363
	s_barrier

.LBB0_588:
	s_add_u32 s12, s10, 0xfffc0080
	s_addc_u32 s13, s11, -1
	s_add_i32 s44, 0, 0x10000
	s_cmp_eq_u32 s43, 12
	s_cselect_b32 s15, s9, s13
	s_cselect_b32 s14, s16, s12
	v_add_u32_e32 v146, s44, v144
	s_cselect_b32 s13, s17, s42
	s_cselect_b32 s12, s35, s37
	s_add_i32 s46, 0, 0x14000
	ds_read_b128 v[140:143], v146
	ds_read_b128 v[158:161], v146 offset:1024
	ds_read_b128 v[162:165], v146 offset:2048
	ds_read_b128 v[166:169], v146 offset:3072
	v_add_u32_e32 v146, s46, v144
	ds_read_b128 v[174:177], v146
	ds_read_b128 v[178:181], v146 offset:1024
	ds_read_b128 v[182:185], v146 offset:2048
	ds_read_b128 v[186:189], v146 offset:3072
	v_lshl_add_u64 v[146:147], s[10:11], 0, v[136:137]
	s_add_i32 m0, s57, 0xc000
	ds_read_b128 v[190:193], v145
	ds_read_b128 v[194:197], v145 offset:1024
	ds_read_b128 v[198:201], v145 offset:2048
	ds_read_b128 v[202:205], v145 offset:3072
	ds_read_b128 v[218:221], v145 offset:4096
	ds_read_b128 v[222:225], v145 offset:5120
	ds_read_b128 v[226:229], v145 offset:6144
	ds_read_b128 v[230:233], v145 offset:7168
	global_load_lds_dwordx4 v[146:147], off
	v_lshl_add_u64 v[146:147], s[10:11], 0, v[138:139]
	s_add_i32 m0, s57, 0xe000
	s_nop 0
	global_load_lds_dwordx4 v[146:147], off
	s_waitcnt vmcnt(8)
	s_waitcnt lgkmcnt(0)
	s_setprio 0
	s_barrier
	s_waitcnt lgkmcnt(0)
	v_mfma_f32_16x16x32_bf16 v[124:127], v[140:143], v[190:193], v[124:127]
	v_mfma_f32_16x16x32_bf16 v[120:123], v[162:165], v[190:193], v[120:123]
	v_mfma_f32_16x16x32_bf16 v[108:111], v[140:143], v[198:201], v[108:111]
	v_mfma_f32_16x16x32_bf16 v[104:107], v[162:165], v[198:201], v[104:107]
	v_mfma_f32_16x16x32_bf16 v[92:95], v[140:143], v[218:221], v[92:95]
	v_mfma_f32_16x16x32_bf16 v[88:91], v[162:165], v[218:221], v[88:91]
	v_mfma_f32_16x16x32_bf16 v[76:79], v[140:143], v[226:229], v[76:79]
	v_mfma_f32_16x16x32_bf16 v[72:75], v[162:165], v[226:229], v[72:75]
	v_mfma_f32_16x16x32_bf16 v[124:127], v[158:161], v[194:197], v[124:127]
	v_mfma_f32_16x16x32_bf16 v[120:123], v[166:169], v[194:197], v[120:123]
	v_mfma_f32_16x16x32_bf16 v[108:111], v[158:161], v[202:205], v[108:111]
	v_mfma_f32_16x16x32_bf16 v[104:107], v[166:169], v[202:205], v[104:107]
	v_mfma_f32_16x16x32_bf16 v[92:95], v[158:161], v[222:225], v[92:95]
	v_mfma_f32_16x16x32_bf16 v[88:91], v[166:169], v[222:225], v[88:91]
	v_mfma_f32_16x16x32_bf16 v[76:79], v[158:161], v[230:233], v[76:79]
	v_mfma_f32_16x16x32_bf16 v[72:75], v[166:169], v[230:233], v[72:75]
	v_mfma_f32_16x16x32_bf16 v[116:119], v[174:177], v[190:193], v[116:119]
	v_mfma_f32_16x16x32_bf16 v[112:115], v[182:185], v[190:193], v[112:115]
	v_mfma_f32_16x16x32_bf16 v[100:103], v[174:177], v[198:201], v[100:103]
	v_mfma_f32_16x16x32_bf16 v[96:99], v[182:185], v[198:201], v[96:99]
	v_mfma_f32_16x16x32_bf16 v[84:87], v[174:177], v[218:221], v[84:87]
	v_mfma_f32_16x16x32_bf16 v[80:83], v[182:185], v[218:221], v[80:83]
	v_mfma_f32_16x16x32_bf16 v[68:71], v[174:177], v[226:229], v[68:71]
	v_mfma_f32_16x16x32_bf16 v[64:67], v[182:185], v[226:229], v[64:67]
	v_mfma_f32_16x16x32_bf16 v[116:119], v[178:181], v[194:197], v[116:119]
	v_mfma_f32_16x16x32_bf16 v[112:115], v[186:189], v[194:197], v[112:115]
	v_mfma_f32_16x16x32_bf16 v[100:103], v[178:181], v[202:205], v[100:103]
	v_mfma_f32_16x16x32_bf16 v[96:99], v[186:189], v[202:205], v[96:99]
	v_mfma_f32_16x16x32_bf16 v[84:87], v[178:181], v[222:225], v[84:87]
	v_mfma_f32_16x16x32_bf16 v[80:83], v[186:189], v[222:225], v[80:83]
	v_mfma_f32_16x16x32_bf16 v[68:71], v[178:181], v[230:233], v[68:71]
	v_mfma_f32_16x16x32_bf16 v[64:67], v[186:189], v[230:233], v[64:67]
	s_barrier
	s_setprio 1
	s_add_i32 s44, s44, s56
	v_lshl_add_u64 v[146:147], s[12:13], 0, v[132:133]
	s_mov_b32 m0, s44
	ds_read_b128 v[190:193], v145 offset:16384
	ds_read_b128 v[194:197], v145 offset:17408
	ds_read_b128 v[198:201], v145 offset:18432
	ds_read_b128 v[202:205], v145 offset:19456
	ds_read_b128 v[218:221], v145 offset:20480
	ds_read_b128 v[222:225], v145 offset:21504
	ds_read_b128 v[226:229], v145 offset:22528
	ds_read_b128 v[230:233], v145 offset:23552
	global_load_lds_dwordx4 v[146:147], off
	s_add_i32 m0, s44, 0x2000
	s_add_u32 s44, s12, 0x40000
	v_lshl_add_u64 v[154:155], s[12:13], 0, v[128:129]
	s_addc_u32 s45, s13, 0
	s_add_i32 s46, s46, s56
	global_load_lds_dwordx4 v[154:155], off
	v_lshl_add_u64 v[156:157], s[44:45], 0, v[132:133]
	s_mov_b32 m0, s46
	v_lshl_add_u64 v[170:171], s[14:15], 0, v[130:131]
	global_load_lds_dwordx4 v[156:157], off
	v_lshl_add_u64 v[156:157], s[44:45], 0, v[128:129]
	s_add_i32 m0, s46, 0x2000
	s_nop 0
	global_load_lds_dwordx4 v[156:157], off
	v_lshl_add_u64 v[156:157], s[14:15], 0, v[134:135]
	s_mov_b32 m0, s57
	s_nop 0
	global_load_lds_dwordx4 v[156:157], off
	s_mov_b32 m0, s58
	s_nop 0
	global_load_lds_dwordx4 v[170:171], off
	s_waitcnt vmcnt(8)
	s_waitcnt lgkmcnt(0)
	s_setprio 0
	s_barrier
	s_waitcnt lgkmcnt(0)
	v_mfma_f32_16x16x32_bf16 v[60:63], v[140:143], v[190:193], v[60:63]
	v_mfma_f32_16x16x32_bf16 v[56:59], v[162:165], v[190:193], v[56:59]
	v_mfma_f32_16x16x32_bf16 v[44:47], v[140:143], v[198:201], v[44:47]
	v_mfma_f32_16x16x32_bf16 v[40:43], v[162:165], v[198:201], v[40:43]
	v_mfma_f32_16x16x32_bf16 v[28:31], v[140:143], v[218:221], v[28:31]
	v_mfma_f32_16x16x32_bf16 v[24:27], v[162:165], v[218:221], v[24:27]
	v_mfma_f32_16x16x32_bf16 v[12:15], v[140:143], v[226:229], v[12:15]
	v_mfma_f32_16x16x32_bf16 v[8:11], v[162:165], v[226:229], v[8:11]
	v_mfma_f32_16x16x32_bf16 v[60:63], v[158:161], v[194:197], v[60:63]
	v_mfma_f32_16x16x32_bf16 v[56:59], v[166:169], v[194:197], v[56:59]
	v_mfma_f32_16x16x32_bf16 v[44:47], v[158:161], v[202:205], v[44:47]
	v_mfma_f32_16x16x32_bf16 v[40:43], v[166:169], v[202:205], v[40:43]
	v_mfma_f32_16x16x32_bf16 v[28:31], v[158:161], v[222:225], v[28:31]
	v_mfma_f32_16x16x32_bf16 v[24:27], v[166:169], v[222:225], v[24:27]
	v_mfma_f32_16x16x32_bf16 v[12:15], v[158:161], v[230:233], v[12:15]
	v_mfma_f32_16x16x32_bf16 v[8:11], v[166:169], v[230:233], v[8:11]
	v_mfma_f32_16x16x32_bf16 v[52:55], v[174:177], v[190:193], v[52:55]
	v_mfma_f32_16x16x32_bf16 v[48:51], v[182:185], v[190:193], v[48:51]
	v_mfma_f32_16x16x32_bf16 v[36:39], v[174:177], v[198:201], v[36:39]
	v_mfma_f32_16x16x32_bf16 v[32:35], v[182:185], v[198:201], v[32:35]
	v_mfma_f32_16x16x32_bf16 v[20:23], v[174:177], v[218:221], v[20:23]
	v_mfma_f32_16x16x32_bf16 v[16:19], v[182:185], v[218:221], v[16:19]
	v_mfma_f32_16x16x32_bf16 v[4:7], v[174:177], v[226:229], v[4:7]
	v_mfma_f32_16x16x32_bf16 v[0:3], v[182:185], v[226:229], v[0:3]
	v_mfma_f32_16x16x32_bf16 v[52:55], v[178:181], v[194:197], v[52:55]
	v_mfma_f32_16x16x32_bf16 v[48:51], v[186:189], v[194:197], v[48:51]
	v_mfma_f32_16x16x32_bf16 v[36:39], v[178:181], v[202:205], v[36:39]
	v_mfma_f32_16x16x32_bf16 v[32:35], v[186:189], v[202:205], v[32:35]
	v_mfma_f32_16x16x32_bf16 v[20:23], v[178:181], v[222:225], v[20:23]
	v_mfma_f32_16x16x32_bf16 v[16:19], v[186:189], v[222:225], v[16:19]
	v_mfma_f32_16x16x32_bf16 v[4:7], v[178:181], v[230:233], v[4:7]
	v_mfma_f32_16x16x32_bf16 v[0:3], v[186:189], v[230:233], v[0:3]
	s_barrier
	s_setprio 1
	s_add_i32 s44, 0, 0x18000
	v_add_u32_e32 v148, s44, v144
	s_add_i32 s45, 0, 0x1c000
	ds_read_b128 v[140:143], v148
	ds_read_b128 v[158:161], v148 offset:1024
	ds_read_b128 v[162:165], v148 offset:2048
	ds_read_b128 v[166:169], v148 offset:3072
	v_add_u32_e32 v148, s45, v144
	ds_read_b128 v[174:177], v148
	ds_read_b128 v[178:181], v148 offset:1024
	ds_read_b128 v[182:185], v148 offset:2048
	ds_read_b128 v[186:189], v148 offset:3072
	s_add_u32 s14, s14, 0x40000
	s_addc_u32 s15, s15, 0
	s_mov_b32 m0, s59
	v_lshl_add_u64 v[212:213], s[14:15], 0, v[134:135]
	ds_read_b128 v[190:193], v145 offset:32768
	ds_read_b128 v[194:197], v145 offset:33792
	ds_read_b128 v[198:201], v145 offset:34816
	ds_read_b128 v[202:205], v145 offset:35840
	ds_read_b128 v[218:221], v145 offset:36864
	ds_read_b128 v[222:225], v145 offset:37888
	ds_read_b128 v[226:229], v145 offset:38912
	ds_read_b128 v[230:233], v145 offset:39936
	global_load_lds_dwordx4 v[212:213], off
	v_lshl_add_u64 v[212:213], s[14:15], 0, v[130:131]
	s_mov_b32 m0, s60
	s_nop 0
	global_load_lds_dwordx4 v[212:213], off
	s_waitcnt vmcnt(8)
	s_waitcnt lgkmcnt(0)
	s_setprio 0
	s_barrier
	s_waitcnt lgkmcnt(0)
	v_mfma_f32_16x16x32_bf16 v[124:127], v[140:143], v[190:193], v[124:127]
	v_mfma_f32_16x16x32_bf16 v[120:123], v[162:165], v[190:193], v[120:123]
	v_mfma_f32_16x16x32_bf16 v[108:111], v[140:143], v[198:201], v[108:111]
	v_mfma_f32_16x16x32_bf16 v[104:107], v[162:165], v[198:201], v[104:107]
	v_mfma_f32_16x16x32_bf16 v[92:95], v[140:143], v[218:221], v[92:95]
	v_mfma_f32_16x16x32_bf16 v[88:91], v[162:165], v[218:221], v[88:91]
	v_mfma_f32_16x16x32_bf16 v[76:79], v[140:143], v[226:229], v[76:79]
	v_mfma_f32_16x16x32_bf16 v[72:75], v[162:165], v[226:229], v[72:75]
	v_mfma_f32_16x16x32_bf16 v[124:127], v[158:161], v[194:197], v[124:127]
	v_mfma_f32_16x16x32_bf16 v[120:123], v[166:169], v[194:197], v[120:123]
	v_mfma_f32_16x16x32_bf16 v[108:111], v[158:161], v[202:205], v[108:111]
	v_mfma_f32_16x16x32_bf16 v[104:107], v[166:169], v[202:205], v[104:107]
	v_mfma_f32_16x16x32_bf16 v[92:95], v[158:161], v[222:225], v[92:95]
	v_mfma_f32_16x16x32_bf16 v[88:91], v[166:169], v[222:225], v[88:91]
	v_mfma_f32_16x16x32_bf16 v[76:79], v[158:161], v[230:233], v[76:79]
	v_mfma_f32_16x16x32_bf16 v[72:75], v[166:169], v[230:233], v[72:75]
	v_mfma_f32_16x16x32_bf16 v[116:119], v[174:177], v[190:193], v[116:119]
	v_mfma_f32_16x16x32_bf16 v[112:115], v[182:185], v[190:193], v[112:115]
	v_mfma_f32_16x16x32_bf16 v[100:103], v[174:177], v[198:201], v[100:103]
	v_mfma_f32_16x16x32_bf16 v[96:99], v[182:185], v[198:201], v[96:99]
	v_mfma_f32_16x16x32_bf16 v[84:87], v[174:177], v[218:221], v[84:87]
	v_mfma_f32_16x16x32_bf16 v[80:83], v[182:185], v[218:221], v[80:83]
	v_mfma_f32_16x16x32_bf16 v[68:71], v[174:177], v[226:229], v[68:71]
	v_mfma_f32_16x16x32_bf16 v[64:67], v[182:185], v[226:229], v[64:67]
	v_mfma_f32_16x16x32_bf16 v[116:119], v[178:181], v[194:197], v[116:119]
	v_mfma_f32_16x16x32_bf16 v[112:115], v[186:189], v[194:197], v[112:115]
	v_mfma_f32_16x16x32_bf16 v[100:103], v[178:181], v[202:205], v[100:103]
	v_mfma_f32_16x16x32_bf16 v[96:99], v[186:189], v[202:205], v[96:99]
	v_mfma_f32_16x16x32_bf16 v[84:87], v[178:181], v[222:225], v[84:87]
	v_mfma_f32_16x16x32_bf16 v[80:83], v[186:189], v[222:225], v[80:83]
	v_mfma_f32_16x16x32_bf16 v[68:71], v[178:181], v[230:233], v[68:71]
	v_mfma_f32_16x16x32_bf16 v[64:67], v[186:189], v[230:233], v[64:67]
	s_barrier
	s_setprio 1
	s_add_i32 s14, s44, s56
	v_lshl_add_u64 v[146:147], v[146:147], 0, s[28:29]
	s_mov_b32 m0, s14
	ds_read_b128 v[190:193], v145 offset:49152
	ds_read_b128 v[194:197], v145 offset:50176
	ds_read_b128 v[198:201], v145 offset:51200
	ds_read_b128 v[202:205], v145 offset:52224
	ds_read_b128 v[218:221], v145 offset:53248
	ds_read_b128 v[222:225], v145 offset:54272
	ds_read_b128 v[226:229], v145 offset:55296
	ds_read_b128 v[230:233], v145 offset:56320
	global_load_lds_dwordx4 v[146:147], off
	s_add_i32 m0, s14, 0x2000
	s_add_u32 s12, s12, 0x40080
	v_lshl_add_u64 v[146:147], v[154:155], 0, s[28:29]
	s_addc_u32 s13, s13, 0
	s_add_i32 s14, s45, s56
	global_load_lds_dwordx4 v[146:147], off
	v_lshl_add_u64 v[146:147], s[12:13], 0, v[132:133]
	s_mov_b32 m0, s14
	s_nop 0
	global_load_lds_dwordx4 v[146:147], off
	v_lshl_add_u64 v[146:147], s[12:13], 0, v[128:129]
	s_add_i32 m0, s14, 0x2000
	s_nop 0
	global_load_lds_dwordx4 v[146:147], off
	v_lshl_add_u64 v[146:147], v[156:157], 0, s[28:29]
	s_mov_b32 m0, s72
	s_nop 0
	global_load_lds_dwordx4 v[146:147], off
	v_lshl_add_u64 v[146:147], v[170:171], 0, s[28:29]
	s_mov_b32 m0, s73
	s_nop 0
	global_load_lds_dwordx4 v[146:147], off
	s_waitcnt vmcnt(8)
	s_waitcnt lgkmcnt(0)
	s_setprio 0
	s_barrier
	s_waitcnt lgkmcnt(0)
	v_mfma_f32_16x16x32_bf16 v[60:63], v[140:143], v[190:193], v[60:63]
	v_mfma_f32_16x16x32_bf16 v[56:59], v[162:165], v[190:193], v[56:59]
	v_mfma_f32_16x16x32_bf16 v[44:47], v[140:143], v[198:201], v[44:47]
	v_mfma_f32_16x16x32_bf16 v[40:43], v[162:165], v[198:201], v[40:43]
	v_mfma_f32_16x16x32_bf16 v[28:31], v[140:143], v[218:221], v[28:31]
	v_mfma_f32_16x16x32_bf16 v[24:27], v[162:165], v[218:221], v[24:27]
	v_mfma_f32_16x16x32_bf16 v[12:15], v[140:143], v[226:229], v[12:15]
	v_mfma_f32_16x16x32_bf16 v[8:11], v[162:165], v[226:229], v[8:11]
	v_mfma_f32_16x16x32_bf16 v[60:63], v[158:161], v[194:197], v[60:63]
	v_mfma_f32_16x16x32_bf16 v[56:59], v[166:169], v[194:197], v[56:59]
	v_mfma_f32_16x16x32_bf16 v[44:47], v[158:161], v[202:205], v[44:47]
	v_mfma_f32_16x16x32_bf16 v[40:43], v[166:169], v[202:205], v[40:43]
	v_mfma_f32_16x16x32_bf16 v[28:31], v[158:161], v[222:225], v[28:31]
	v_mfma_f32_16x16x32_bf16 v[24:27], v[166:169], v[222:225], v[24:27]
	v_mfma_f32_16x16x32_bf16 v[12:15], v[158:161], v[230:233], v[12:15]
	v_mfma_f32_16x16x32_bf16 v[8:11], v[166:169], v[230:233], v[8:11]
	v_mfma_f32_16x16x32_bf16 v[52:55], v[174:177], v[190:193], v[52:55]
	v_mfma_f32_16x16x32_bf16 v[48:51], v[182:185], v[190:193], v[48:51]
	v_mfma_f32_16x16x32_bf16 v[36:39], v[174:177], v[198:201], v[36:39]
	v_mfma_f32_16x16x32_bf16 v[32:35], v[182:185], v[198:201], v[32:35]
	v_mfma_f32_16x16x32_bf16 v[20:23], v[174:177], v[218:221], v[20:23]
	v_mfma_f32_16x16x32_bf16 v[16:19], v[182:185], v[218:221], v[16:19]
	v_mfma_f32_16x16x32_bf16 v[4:7], v[174:177], v[226:229], v[4:7]
	v_mfma_f32_16x16x32_bf16 v[0:3], v[182:185], v[226:229], v[0:3]
	v_mfma_f32_16x16x32_bf16 v[52:55], v[178:181], v[194:197], v[52:55]
	v_mfma_f32_16x16x32_bf16 v[48:51], v[186:189], v[194:197], v[48:51]
	v_mfma_f32_16x16x32_bf16 v[36:39], v[178:181], v[202:205], v[36:39]
	v_mfma_f32_16x16x32_bf16 v[32:35], v[186:189], v[202:205], v[32:35]
	v_mfma_f32_16x16x32_bf16 v[20:23], v[178:181], v[222:225], v[20:23]
	v_mfma_f32_16x16x32_bf16 v[16:19], v[186:189], v[222:225], v[16:19]
	v_mfma_f32_16x16x32_bf16 v[4:7], v[178:181], v[230:233], v[4:7]
	v_mfma_f32_16x16x32_bf16 v[0:3], v[186:189], v[230:233], v[0:3]
	s_barrier
	s_setprio 1
	s_add_i32 s43, s43, 2
	s_add_u32 s10, s10, 0x100
	s_addc_u32 s11, s11, 0
	s_add_u32 s37, s37, 0x100
	s_addc_u32 s42, s42, 0
	s_cmp_gt_u32 s43, 13
	s_cbranch_scc0 .LBB0_588
	s_setprio 0
	s_and_b64 vcc, exec, s[26:27]
	s_cbranch_vccz .LBB0_591
	s_barrier

.LBB0_764:
	s_add_u32 s30, s26, 0xfffc0080
	s_addc_u32 s31, s27, -1
	s_add_i32 s53, 0, 0x10000
	s_cmp_eq_u32 s52, 12
	s_cselect_b32 s35, s21, s31
	s_cselect_b32 s34, s48, s30
	s_cselect_b32 s31, s19, s51
	s_cselect_b32 s30, s49, s50
	s_add_i32 s56, 0, 0x14000
	v_add_u32_e32 v140, s53, v173
	v_add_u32_e32 v150, s56, v173
	ds_read_b128 v[128:131], v140
	ds_read_b128 v[132:135], v140 offset:1024
	ds_read_b128 v[136:139], v140 offset:2048
	ds_read_b128 v[140:143], v140 offset:3072
	ds_read_b128 v[164:167], v150
	ds_read_b128 v[168:171], v150 offset:1024
	ds_read_b128 v[176:179], v150 offset:2048
	ds_read_b128 v[180:183], v150 offset:3072
	v_lshl_add_u64 v[154:155], s[26:27], 0, v[160:161]
	s_add_i32 m0, s37, 0xc000
	ds_read_b128 v[184:187], v174
	ds_read_b128 v[188:191], v174 offset:1024
	ds_read_b128 v[192:195], v174 offset:2048
	ds_read_b128 v[196:199], v174 offset:3072
	ds_read_b128 v[200:203], v174 offset:4096
	ds_read_b128 v[218:221], v174 offset:5120
	ds_read_b128 v[222:225], v174 offset:6144
	ds_read_b128 v[226:229], v174 offset:7168
	global_load_lds_dwordx4 v[154:155], off
	v_lshl_add_u64 v[154:155], s[26:27], 0, v[162:163]
	s_add_i32 m0, s37, 0xe000
	s_nop 0
	global_load_lds_dwordx4 v[154:155], off
	s_waitcnt vmcnt(8)
	s_waitcnt lgkmcnt(0)
	s_setprio 0
	s_barrier
	s_waitcnt lgkmcnt(0)
	v_mfma_f32_16x16x32_bf16 v[124:127], v[128:131], v[184:187], v[124:127]
	v_mfma_f32_16x16x32_bf16 v[92:95], v[136:139], v[184:187], v[92:95]
	v_mfma_f32_16x16x32_bf16 v[120:123], v[128:131], v[192:195], v[120:123]
	v_mfma_f32_16x16x32_bf16 v[88:91], v[136:139], v[192:195], v[88:91]
	v_mfma_f32_16x16x32_bf16 v[116:119], v[128:131], v[200:203], v[116:119]
	v_mfma_f32_16x16x32_bf16 v[84:87], v[136:139], v[200:203], v[84:87]
	v_mfma_f32_16x16x32_bf16 v[112:115], v[128:131], v[222:225], v[112:115]
	v_mfma_f32_16x16x32_bf16 v[80:83], v[136:139], v[222:225], v[80:83]
	v_mfma_f32_16x16x32_bf16 v[124:127], v[132:135], v[188:191], v[124:127]
	v_mfma_f32_16x16x32_bf16 v[92:95], v[140:143], v[188:191], v[92:95]
	v_mfma_f32_16x16x32_bf16 v[120:123], v[132:135], v[196:199], v[120:123]
	v_mfma_f32_16x16x32_bf16 v[88:91], v[140:143], v[196:199], v[88:91]
	v_mfma_f32_16x16x32_bf16 v[116:119], v[132:135], v[218:221], v[116:119]
	v_mfma_f32_16x16x32_bf16 v[84:87], v[140:143], v[218:221], v[84:87]
	v_mfma_f32_16x16x32_bf16 v[112:115], v[132:135], v[226:229], v[112:115]
	v_mfma_f32_16x16x32_bf16 v[80:83], v[140:143], v[226:229], v[80:83]
	v_mfma_f32_16x16x32_bf16 v[60:63], v[164:167], v[184:187], v[60:63]
	v_mfma_f32_16x16x32_bf16 v[28:31], v[176:179], v[184:187], v[28:31]
	v_mfma_f32_16x16x32_bf16 v[56:59], v[164:167], v[192:195], v[56:59]
	v_mfma_f32_16x16x32_bf16 v[24:27], v[176:179], v[192:195], v[24:27]
	v_mfma_f32_16x16x32_bf16 v[52:55], v[164:167], v[200:203], v[52:55]
	v_mfma_f32_16x16x32_bf16 v[20:23], v[176:179], v[200:203], v[20:23]
	v_mfma_f32_16x16x32_bf16 v[48:51], v[164:167], v[222:225], v[48:51]
	v_mfma_f32_16x16x32_bf16 v[16:19], v[176:179], v[222:225], v[16:19]
	v_mfma_f32_16x16x32_bf16 v[60:63], v[168:171], v[188:191], v[60:63]
	v_mfma_f32_16x16x32_bf16 v[28:31], v[180:183], v[188:191], v[28:31]
	v_mfma_f32_16x16x32_bf16 v[56:59], v[168:171], v[196:199], v[56:59]
	v_mfma_f32_16x16x32_bf16 v[24:27], v[180:183], v[196:199], v[24:27]
	v_mfma_f32_16x16x32_bf16 v[52:55], v[168:171], v[218:221], v[52:55]
	v_mfma_f32_16x16x32_bf16 v[20:23], v[180:183], v[218:221], v[20:23]
	v_mfma_f32_16x16x32_bf16 v[48:51], v[168:171], v[226:229], v[48:51]
	v_mfma_f32_16x16x32_bf16 v[16:19], v[180:183], v[226:229], v[16:19]
	s_barrier
	s_setprio 1
	s_add_i32 s53, s53, s36
	v_lshl_add_u64 v[154:155], s[30:31], 0, v[158:159]
	s_mov_b32 m0, s53
	ds_read_b128 v[184:187], v174 offset:16384
	ds_read_b128 v[188:191], v174 offset:17408
	ds_read_b128 v[192:195], v174 offset:18432
	ds_read_b128 v[196:199], v174 offset:19456
	ds_read_b128 v[200:203], v174 offset:20480
	ds_read_b128 v[218:221], v174 offset:21504
	ds_read_b128 v[222:225], v174 offset:22528
	ds_read_b128 v[226:229], v174 offset:23552
	global_load_lds_dwordx4 v[154:155], off
	s_add_i32 m0, s53, 0x2000
	s_add_u32 s54, s30, 0x40000
	v_lshl_add_u64 v[156:157], s[30:31], 0, v[144:145]
	s_addc_u32 s55, s31, 0
	s_add_i32 s53, s56, s36
	global_load_lds_dwordx4 v[156:157], off
	v_lshl_add_u64 v[204:205], s[54:55], 0, v[158:159]
	s_mov_b32 m0, s53
	v_lshl_add_u64 v[212:213], s[34:35], 0, v[146:147]
	global_load_lds_dwordx4 v[204:205], off
	v_lshl_add_u64 v[204:205], s[54:55], 0, v[144:145]
	s_add_i32 m0, s53, 0x2000
	s_nop 0
	global_load_lds_dwordx4 v[204:205], off
	v_lshl_add_u64 v[204:205], s[34:35], 0, v[148:149]
	s_mov_b32 m0, s37
	s_nop 0
	global_load_lds_dwordx4 v[204:205], off
	s_mov_b32 m0, s38
	s_nop 0
	global_load_lds_dwordx4 v[212:213], off
	s_waitcnt vmcnt(8)
	s_waitcnt lgkmcnt(0)
	s_setprio 0
	s_barrier
	s_waitcnt lgkmcnt(0)
	v_mfma_f32_16x16x32_bf16 v[108:111], v[128:131], v[184:187], v[108:111]
	v_mfma_f32_16x16x32_bf16 v[76:79], v[136:139], v[184:187], v[76:79]
	v_mfma_f32_16x16x32_bf16 v[104:107], v[128:131], v[192:195], v[104:107]
	v_mfma_f32_16x16x32_bf16 v[72:75], v[136:139], v[192:195], v[72:75]
	v_mfma_f32_16x16x32_bf16 v[100:103], v[128:131], v[200:203], v[100:103]
	v_mfma_f32_16x16x32_bf16 v[68:71], v[136:139], v[200:203], v[68:71]
	v_mfma_f32_16x16x32_bf16 v[96:99], v[128:131], v[222:225], v[96:99]
	v_mfma_f32_16x16x32_bf16 v[64:67], v[136:139], v[222:225], v[64:67]
	v_mfma_f32_16x16x32_bf16 v[108:111], v[132:135], v[188:191], v[108:111]
	v_mfma_f32_16x16x32_bf16 v[76:79], v[140:143], v[188:191], v[76:79]
	v_mfma_f32_16x16x32_bf16 v[104:107], v[132:135], v[196:199], v[104:107]
	v_mfma_f32_16x16x32_bf16 v[72:75], v[140:143], v[196:199], v[72:75]
	v_mfma_f32_16x16x32_bf16 v[100:103], v[132:135], v[218:221], v[100:103]
	v_mfma_f32_16x16x32_bf16 v[68:71], v[140:143], v[218:221], v[68:71]
	v_mfma_f32_16x16x32_bf16 v[96:99], v[132:135], v[226:229], v[96:99]
	v_mfma_f32_16x16x32_bf16 v[64:67], v[140:143], v[226:229], v[64:67]
	v_mfma_f32_16x16x32_bf16 v[44:47], v[164:167], v[184:187], v[44:47]
	v_mfma_f32_16x16x32_bf16 v[12:15], v[176:179], v[184:187], v[12:15]
	v_mfma_f32_16x16x32_bf16 v[40:43], v[164:167], v[192:195], v[40:43]
	v_mfma_f32_16x16x32_bf16 v[8:11], v[176:179], v[192:195], v[8:11]
	v_mfma_f32_16x16x32_bf16 v[36:39], v[164:167], v[200:203], v[36:39]
	v_mfma_f32_16x16x32_bf16 v[4:7], v[176:179], v[200:203], v[4:7]
	v_mfma_f32_16x16x32_bf16 v[32:35], v[164:167], v[222:225], v[32:35]
	v_mfma_f32_16x16x32_bf16 v[0:3], v[176:179], v[222:225], v[0:3]
	v_mfma_f32_16x16x32_bf16 v[44:47], v[168:171], v[188:191], v[44:47]
	v_mfma_f32_16x16x32_bf16 v[12:15], v[180:183], v[188:191], v[12:15]
	v_mfma_f32_16x16x32_bf16 v[40:43], v[168:171], v[196:199], v[40:43]
	v_mfma_f32_16x16x32_bf16 v[8:11], v[180:183], v[196:199], v[8:11]
	v_mfma_f32_16x16x32_bf16 v[36:39], v[168:171], v[218:221], v[36:39]
	v_mfma_f32_16x16x32_bf16 v[4:7], v[180:183], v[218:221], v[4:7]
	v_mfma_f32_16x16x32_bf16 v[32:35], v[168:171], v[226:229], v[32:35]
	v_mfma_f32_16x16x32_bf16 v[0:3], v[180:183], v[226:229], v[0:3]
	s_barrier
	s_setprio 1
	s_add_i32 s53, 0, 0x18000
	s_add_i32 s54, 0, 0x1c000
	v_add_u32_e32 v140, s53, v173
	v_add_u32_e32 v150, s54, v173
	ds_read_b128 v[128:131], v140
	ds_read_b128 v[132:135], v140 offset:1024
	ds_read_b128 v[136:139], v140 offset:2048
	ds_read_b128 v[140:143], v140 offset:3072
	ds_read_b128 v[164:167], v150
	ds_read_b128 v[168:171], v150 offset:1024
	ds_read_b128 v[176:179], v150 offset:2048
	ds_read_b128 v[180:183], v150 offset:3072
	s_add_u32 s34, s34, 0x40000
	s_addc_u32 s35, s35, 0
	s_mov_b32 m0, s39
	v_lshl_add_u64 v[214:215], s[34:35], 0, v[148:149]
	ds_read_b128 v[184:187], v174 offset:32768
	ds_read_b128 v[188:191], v174 offset:33792
	ds_read_b128 v[192:195], v174 offset:34816
	ds_read_b128 v[196:199], v174 offset:35840
	ds_read_b128 v[200:203], v174 offset:36864
	ds_read_b128 v[218:221], v174 offset:37888
	ds_read_b128 v[222:225], v174 offset:38912
	ds_read_b128 v[226:229], v174 offset:39936
	global_load_lds_dwordx4 v[214:215], off
	v_lshl_add_u64 v[214:215], s[34:35], 0, v[146:147]
	s_mov_b32 m0, s40
	s_nop 0
	global_load_lds_dwordx4 v[214:215], off
	s_waitcnt vmcnt(8)
	s_waitcnt lgkmcnt(0)
	s_setprio 0
	s_barrier
	s_waitcnt lgkmcnt(0)
	v_mfma_f32_16x16x32_bf16 v[124:127], v[128:131], v[184:187], v[124:127]
	v_mfma_f32_16x16x32_bf16 v[92:95], v[136:139], v[184:187], v[92:95]
	v_mfma_f32_16x16x32_bf16 v[120:123], v[128:131], v[192:195], v[120:123]
	v_mfma_f32_16x16x32_bf16 v[88:91], v[136:139], v[192:195], v[88:91]
	v_mfma_f32_16x16x32_bf16 v[116:119], v[128:131], v[200:203], v[116:119]
	v_mfma_f32_16x16x32_bf16 v[84:87], v[136:139], v[200:203], v[84:87]
	v_mfma_f32_16x16x32_bf16 v[112:115], v[128:131], v[222:225], v[112:115]
	v_mfma_f32_16x16x32_bf16 v[80:83], v[136:139], v[222:225], v[80:83]
	v_mfma_f32_16x16x32_bf16 v[124:127], v[132:135], v[188:191], v[124:127]
	v_mfma_f32_16x16x32_bf16 v[92:95], v[140:143], v[188:191], v[92:95]
	v_mfma_f32_16x16x32_bf16 v[120:123], v[132:135], v[196:199], v[120:123]
	v_mfma_f32_16x16x32_bf16 v[88:91], v[140:143], v[196:199], v[88:91]
	v_mfma_f32_16x16x32_bf16 v[116:119], v[132:135], v[218:221], v[116:119]
	v_mfma_f32_16x16x32_bf16 v[84:87], v[140:143], v[218:221], v[84:87]
	v_mfma_f32_16x16x32_bf16 v[112:115], v[132:135], v[226:229], v[112:115]
	v_mfma_f32_16x16x32_bf16 v[80:83], v[140:143], v[226:229], v[80:83]
	v_mfma_f32_16x16x32_bf16 v[60:63], v[164:167], v[184:187], v[60:63]
	v_mfma_f32_16x16x32_bf16 v[28:31], v[176:179], v[184:187], v[28:31]
	v_mfma_f32_16x16x32_bf16 v[56:59], v[164:167], v[192:195], v[56:59]
	v_mfma_f32_16x16x32_bf16 v[24:27], v[176:179], v[192:195], v[24:27]
	v_mfma_f32_16x16x32_bf16 v[52:55], v[164:167], v[200:203], v[52:55]
	v_mfma_f32_16x16x32_bf16 v[20:23], v[176:179], v[200:203], v[20:23]
	v_mfma_f32_16x16x32_bf16 v[48:51], v[164:167], v[222:225], v[48:51]
	v_mfma_f32_16x16x32_bf16 v[16:19], v[176:179], v[222:225], v[16:19]
	v_mfma_f32_16x16x32_bf16 v[60:63], v[168:171], v[188:191], v[60:63]
	v_mfma_f32_16x16x32_bf16 v[28:31], v[180:183], v[188:191], v[28:31]
	v_mfma_f32_16x16x32_bf16 v[56:59], v[168:171], v[196:199], v[56:59]
	v_mfma_f32_16x16x32_bf16 v[24:27], v[180:183], v[196:199], v[24:27]
	v_mfma_f32_16x16x32_bf16 v[52:55], v[168:171], v[218:221], v[52:55]
	v_mfma_f32_16x16x32_bf16 v[20:23], v[180:183], v[218:221], v[20:23]
	v_mfma_f32_16x16x32_bf16 v[48:51], v[168:171], v[226:229], v[48:51]
	v_mfma_f32_16x16x32_bf16 v[16:19], v[180:183], v[226:229], v[16:19]
	s_barrier
	s_setprio 1
	s_add_i32 s34, s53, s36
	v_lshl_add_u64 v[154:155], v[154:155], 0, s[28:29]
	s_mov_b32 m0, s34
	ds_read_b128 v[184:187], v174 offset:49152
	ds_read_b128 v[188:191], v174 offset:50176
	ds_read_b128 v[192:195], v174 offset:51200
	ds_read_b128 v[196:199], v174 offset:52224
	ds_read_b128 v[200:203], v174 offset:53248
	ds_read_b128 v[218:221], v174 offset:54272
	ds_read_b128 v[222:225], v174 offset:55296
	ds_read_b128 v[226:229], v174 offset:56320
	global_load_lds_dwordx4 v[154:155], off
	s_add_i32 m0, s34, 0x2000
	s_add_u32 s30, s30, 0x40080
	v_lshl_add_u64 v[154:155], v[156:157], 0, s[28:29]
	s_addc_u32 s31, s31, 0
	s_add_i32 s34, s54, s36
	global_load_lds_dwordx4 v[154:155], off
	v_lshl_add_u64 v[154:155], s[30:31], 0, v[158:159]
	s_mov_b32 m0, s34
	s_nop 0
	global_load_lds_dwordx4 v[154:155], off
	v_lshl_add_u64 v[154:155], s[30:31], 0, v[144:145]
	s_add_i32 m0, s34, 0x2000
	s_nop 0
	global_load_lds_dwordx4 v[154:155], off
	v_lshl_add_u64 v[154:155], v[204:205], 0, s[28:29]
	s_mov_b32 m0, s43
	s_nop 0
	global_load_lds_dwordx4 v[154:155], off
	v_lshl_add_u64 v[154:155], v[212:213], 0, s[28:29]
	s_mov_b32 m0, s44
	s_nop 0
	global_load_lds_dwordx4 v[154:155], off
	s_waitcnt vmcnt(8)
	s_waitcnt lgkmcnt(0)
	s_setprio 0
	s_barrier
	s_waitcnt lgkmcnt(0)
	v_mfma_f32_16x16x32_bf16 v[108:111], v[128:131], v[184:187], v[108:111]
	v_mfma_f32_16x16x32_bf16 v[76:79], v[136:139], v[184:187], v[76:79]
	v_mfma_f32_16x16x32_bf16 v[104:107], v[128:131], v[192:195], v[104:107]
	v_mfma_f32_16x16x32_bf16 v[72:75], v[136:139], v[192:195], v[72:75]
	v_mfma_f32_16x16x32_bf16 v[100:103], v[128:131], v[200:203], v[100:103]
	v_mfma_f32_16x16x32_bf16 v[68:71], v[136:139], v[200:203], v[68:71]
	v_mfma_f32_16x16x32_bf16 v[96:99], v[128:131], v[222:225], v[96:99]
	v_mfma_f32_16x16x32_bf16 v[64:67], v[136:139], v[222:225], v[64:67]
	v_mfma_f32_16x16x32_bf16 v[108:111], v[132:135], v[188:191], v[108:111]
	v_mfma_f32_16x16x32_bf16 v[76:79], v[140:143], v[188:191], v[76:79]
	v_mfma_f32_16x16x32_bf16 v[104:107], v[132:135], v[196:199], v[104:107]
	v_mfma_f32_16x16x32_bf16 v[72:75], v[140:143], v[196:199], v[72:75]
	v_mfma_f32_16x16x32_bf16 v[100:103], v[132:135], v[218:221], v[100:103]
	v_mfma_f32_16x16x32_bf16 v[68:71], v[140:143], v[218:221], v[68:71]
	v_mfma_f32_16x16x32_bf16 v[96:99], v[132:135], v[226:229], v[96:99]
	v_mfma_f32_16x16x32_bf16 v[64:67], v[140:143], v[226:229], v[64:67]
	v_mfma_f32_16x16x32_bf16 v[44:47], v[164:167], v[184:187], v[44:47]
	v_mfma_f32_16x16x32_bf16 v[12:15], v[176:179], v[184:187], v[12:15]
	v_mfma_f32_16x16x32_bf16 v[40:43], v[164:167], v[192:195], v[40:43]
	v_mfma_f32_16x16x32_bf16 v[8:11], v[176:179], v[192:195], v[8:11]
	v_mfma_f32_16x16x32_bf16 v[36:39], v[164:167], v[200:203], v[36:39]
	v_mfma_f32_16x16x32_bf16 v[4:7], v[176:179], v[200:203], v[4:7]
	v_mfma_f32_16x16x32_bf16 v[32:35], v[164:167], v[222:225], v[32:35]
	v_mfma_f32_16x16x32_bf16 v[0:3], v[176:179], v[222:225], v[0:3]
	v_mfma_f32_16x16x32_bf16 v[44:47], v[168:171], v[188:191], v[44:47]
	v_mfma_f32_16x16x32_bf16 v[12:15], v[180:183], v[188:191], v[12:15]
	v_mfma_f32_16x16x32_bf16 v[40:43], v[168:171], v[196:199], v[40:43]
	v_mfma_f32_16x16x32_bf16 v[8:11], v[180:183], v[196:199], v[8:11]
	v_mfma_f32_16x16x32_bf16 v[36:39], v[168:171], v[218:221], v[36:39]
	v_mfma_f32_16x16x32_bf16 v[4:7], v[180:183], v[218:221], v[4:7]
	v_mfma_f32_16x16x32_bf16 v[32:35], v[168:171], v[226:229], v[32:35]
	v_mfma_f32_16x16x32_bf16 v[0:3], v[180:183], v[226:229], v[0:3]
	s_barrier
	s_setprio 1
	s_add_i32 s52, s52, 2
	s_add_u32 s26, s26, 0x100
	s_addc_u32 s27, s27, 0
	s_add_u32 s50, s50, 0x100
	s_addc_u32 s51, s51, 0
	s_cmp_gt_u32 s52, 13
	s_cbranch_scc0 .LBB0_764
	s_setprio 0
	s_and_b64 vcc, exec, s[16:17]
	s_mov_b32 s49, s57
	s_cbranch_vccz .LBB0_767
	s_barrier

.LBB0_1335:
	s_add_u32 s22, s8, 0xfffe0080
	s_addc_u32 s23, s9, -1
	s_add_i32 s54, 0, 0x10000
	s_cmp_eq_u32 s53, 4
	s_cselect_b32 s25, s17, s23
	s_cselect_b32 s24, s49, s22
	v_add_u32_e32 v146, s54, v158
	s_cselect_b32 s23, s15, s52
	s_cselect_b32 s22, s50, s51
	s_add_i32 s56, 0, 0x14000
	ds_read_b128 v[138:141], v146
	ds_read_b128 v[142:145], v146 offset:1024
	ds_read_b128 v[154:157], v146 offset:2048
	ds_read_b128 v[160:163], v146 offset:3072
	v_add_u32_e32 v146, s56, v158
	ds_read_b128 v[164:167], v146
	ds_read_b128 v[168:171], v146 offset:1024
	ds_read_b128 v[172:175], v146 offset:2048
	ds_read_b128 v[176:179], v146 offset:3072
	v_lshl_add_u64 v[146:147], s[8:9], 0, v[134:135]
	s_add_i32 m0, s38, 0xc000
	ds_read_b128 v[180:183], v159
	ds_read_b128 v[184:187], v159 offset:1024
	ds_read_b128 v[188:191], v159 offset:2048
	ds_read_b128 v[192:195], v159 offset:3072
	ds_read_b128 v[196:199], v159 offset:4096
	ds_read_b128 v[200:203], v159 offset:5120
	ds_read_b128 v[212:215], v159 offset:6144
	ds_read_b128 v[220:223], v159 offset:7168
	global_load_lds_dwordx4 v[146:147], off
	v_lshl_add_u64 v[146:147], s[8:9], 0, v[136:137]
	s_add_i32 m0, s38, 0xe000
	s_nop 0
	global_load_lds_dwordx4 v[146:147], off
	s_waitcnt vmcnt(8)
	s_waitcnt lgkmcnt(0)
	s_setprio 0
	s_barrier
	s_waitcnt lgkmcnt(0)
	v_mfma_f32_16x16x32_bf16 v[124:127], v[138:141], v[180:183], v[124:127]
	v_mfma_f32_16x16x32_bf16 v[120:123], v[154:157], v[180:183], v[120:123]
	v_mfma_f32_16x16x32_bf16 v[108:111], v[138:141], v[188:191], v[108:111]
	v_mfma_f32_16x16x32_bf16 v[104:107], v[154:157], v[188:191], v[104:107]
	v_mfma_f32_16x16x32_bf16 v[92:95], v[138:141], v[196:199], v[92:95]
	v_mfma_f32_16x16x32_bf16 v[88:91], v[154:157], v[196:199], v[88:91]
	v_mfma_f32_16x16x32_bf16 v[76:79], v[138:141], v[212:215], v[76:79]
	v_mfma_f32_16x16x32_bf16 v[72:75], v[154:157], v[212:215], v[72:75]
	v_mfma_f32_16x16x32_bf16 v[124:127], v[142:145], v[184:187], v[124:127]
	v_mfma_f32_16x16x32_bf16 v[120:123], v[160:163], v[184:187], v[120:123]
	v_mfma_f32_16x16x32_bf16 v[108:111], v[142:145], v[192:195], v[108:111]
	v_mfma_f32_16x16x32_bf16 v[104:107], v[160:163], v[192:195], v[104:107]
	v_mfma_f32_16x16x32_bf16 v[92:95], v[142:145], v[200:203], v[92:95]
	v_mfma_f32_16x16x32_bf16 v[88:91], v[160:163], v[200:203], v[88:91]
	v_mfma_f32_16x16x32_bf16 v[76:79], v[142:145], v[220:223], v[76:79]
	v_mfma_f32_16x16x32_bf16 v[72:75], v[160:163], v[220:223], v[72:75]
	v_mfma_f32_16x16x32_bf16 v[116:119], v[164:167], v[180:183], v[116:119]
	v_mfma_f32_16x16x32_bf16 v[112:115], v[172:175], v[180:183], v[112:115]
	v_mfma_f32_16x16x32_bf16 v[100:103], v[164:167], v[188:191], v[100:103]
	v_mfma_f32_16x16x32_bf16 v[96:99], v[172:175], v[188:191], v[96:99]
	v_mfma_f32_16x16x32_bf16 v[84:87], v[164:167], v[196:199], v[84:87]
	v_mfma_f32_16x16x32_bf16 v[80:83], v[172:175], v[196:199], v[80:83]
	v_mfma_f32_16x16x32_bf16 v[68:71], v[164:167], v[212:215], v[68:71]
	v_mfma_f32_16x16x32_bf16 v[64:67], v[172:175], v[212:215], v[64:67]
	v_mfma_f32_16x16x32_bf16 v[116:119], v[168:171], v[184:187], v[116:119]
	v_mfma_f32_16x16x32_bf16 v[112:115], v[176:179], v[184:187], v[112:115]
	v_mfma_f32_16x16x32_bf16 v[100:103], v[168:171], v[192:195], v[100:103]
	v_mfma_f32_16x16x32_bf16 v[96:99], v[176:179], v[192:195], v[96:99]
	v_mfma_f32_16x16x32_bf16 v[84:87], v[168:171], v[200:203], v[84:87]
	v_mfma_f32_16x16x32_bf16 v[80:83], v[176:179], v[200:203], v[80:83]
	v_mfma_f32_16x16x32_bf16 v[68:71], v[168:171], v[220:223], v[68:71]
	v_mfma_f32_16x16x32_bf16 v[64:67], v[176:179], v[220:223], v[64:67]
	s_barrier
	s_setprio 1
	s_add_i32 s54, s54, s37
	v_lshl_add_u64 v[146:147], s[22:23], 0, v[148:149]
	s_mov_b32 m0, s54
	ds_read_b128 v[180:183], v159 offset:16384
	ds_read_b128 v[184:187], v159 offset:17408
	ds_read_b128 v[188:191], v159 offset:18432
	ds_read_b128 v[192:195], v159 offset:19456
	ds_read_b128 v[196:199], v159 offset:20480
	ds_read_b128 v[200:203], v159 offset:21504
	ds_read_b128 v[212:215], v159 offset:22528
	ds_read_b128 v[220:223], v159 offset:23552
	global_load_lds_dwordx4 v[146:147], off
	s_add_i32 m0, s54, 0x2000
	s_add_u32 s54, s22, 0x20000
	v_lshl_add_u64 v[150:151], s[22:23], 0, v[128:129]
	s_addc_u32 s55, s23, 0
	s_add_i32 s56, s56, s37
	global_load_lds_dwordx4 v[150:151], off
	v_lshl_add_u64 v[152:153], s[54:55], 0, v[148:149]
	s_mov_b32 m0, s56
	v_lshl_add_u64 v[204:205], s[24:25], 0, v[130:131]
	global_load_lds_dwordx4 v[152:153], off
	v_lshl_add_u64 v[152:153], s[54:55], 0, v[128:129]
	s_add_i32 m0, s56, 0x2000
	s_nop 0
	global_load_lds_dwordx4 v[152:153], off
	v_lshl_add_u64 v[152:153], s[24:25], 0, v[132:133]
	s_mov_b32 m0, s38
	s_nop 0
	global_load_lds_dwordx4 v[152:153], off
	s_mov_b32 m0, s39
	s_nop 0
	global_load_lds_dwordx4 v[204:205], off
	s_waitcnt vmcnt(8)
	s_waitcnt lgkmcnt(0)
	s_setprio 0
	s_barrier
	s_waitcnt lgkmcnt(0)
	v_mfma_f32_16x16x32_bf16 v[60:63], v[138:141], v[180:183], v[60:63]
	v_mfma_f32_16x16x32_bf16 v[56:59], v[154:157], v[180:183], v[56:59]
	v_mfma_f32_16x16x32_bf16 v[44:47], v[138:141], v[188:191], v[44:47]
	v_mfma_f32_16x16x32_bf16 v[40:43], v[154:157], v[188:191], v[40:43]
	v_mfma_f32_16x16x32_bf16 v[28:31], v[138:141], v[196:199], v[28:31]
	v_mfma_f32_16x16x32_bf16 v[24:27], v[154:157], v[196:199], v[24:27]
	v_mfma_f32_16x16x32_bf16 v[12:15], v[138:141], v[212:215], v[12:15]
	v_mfma_f32_16x16x32_bf16 v[8:11], v[154:157], v[212:215], v[8:11]
	v_mfma_f32_16x16x32_bf16 v[60:63], v[142:145], v[184:187], v[60:63]
	v_mfma_f32_16x16x32_bf16 v[56:59], v[160:163], v[184:187], v[56:59]
	v_mfma_f32_16x16x32_bf16 v[44:47], v[142:145], v[192:195], v[44:47]
	v_mfma_f32_16x16x32_bf16 v[40:43], v[160:163], v[192:195], v[40:43]
	v_mfma_f32_16x16x32_bf16 v[28:31], v[142:145], v[200:203], v[28:31]
	v_mfma_f32_16x16x32_bf16 v[24:27], v[160:163], v[200:203], v[24:27]
	v_mfma_f32_16x16x32_bf16 v[12:15], v[142:145], v[220:223], v[12:15]
	v_mfma_f32_16x16x32_bf16 v[8:11], v[160:163], v[220:223], v[8:11]
	v_mfma_f32_16x16x32_bf16 v[52:55], v[164:167], v[180:183], v[52:55]
	v_mfma_f32_16x16x32_bf16 v[48:51], v[172:175], v[180:183], v[48:51]
	v_mfma_f32_16x16x32_bf16 v[36:39], v[164:167], v[188:191], v[36:39]
	v_mfma_f32_16x16x32_bf16 v[32:35], v[172:175], v[188:191], v[32:35]
	v_mfma_f32_16x16x32_bf16 v[20:23], v[164:167], v[196:199], v[20:23]
	v_mfma_f32_16x16x32_bf16 v[16:19], v[172:175], v[196:199], v[16:19]
	v_mfma_f32_16x16x32_bf16 v[4:7], v[164:167], v[212:215], v[4:7]
	v_mfma_f32_16x16x32_bf16 v[0:3], v[172:175], v[212:215], v[0:3]
	v_mfma_f32_16x16x32_bf16 v[52:55], v[168:171], v[184:187], v[52:55]
	v_mfma_f32_16x16x32_bf16 v[48:51], v[176:179], v[184:187], v[48:51]
	v_mfma_f32_16x16x32_bf16 v[36:39], v[168:171], v[192:195], v[36:39]
	v_mfma_f32_16x16x32_bf16 v[32:35], v[176:179], v[192:195], v[32:35]
	v_mfma_f32_16x16x32_bf16 v[20:23], v[168:171], v[200:203], v[20:23]
	v_mfma_f32_16x16x32_bf16 v[16:19], v[176:179], v[200:203], v[16:19]
	v_mfma_f32_16x16x32_bf16 v[4:7], v[168:171], v[220:223], v[4:7]
	v_mfma_f32_16x16x32_bf16 v[0:3], v[176:179], v[220:223], v[0:3]
	s_barrier
	s_setprio 1
	s_add_i32 s54, 0, 0x18000
	s_add_i32 s55, 0, 0x1c000
	v_add_u32_e32 v160, s54, v158
	v_add_u32_e32 v176, s55, v158
	ds_read_b128 v[138:141], v160
	ds_read_b128 v[142:145], v160 offset:1024
	ds_read_b128 v[154:157], v160 offset:2048
	ds_read_b128 v[160:163], v160 offset:3072
	ds_read_b128 v[164:167], v176
	ds_read_b128 v[168:171], v176 offset:1024
	ds_read_b128 v[172:175], v176 offset:2048
	ds_read_b128 v[176:179], v176 offset:3072
	s_add_u32 s24, s24, 0x20000
	s_addc_u32 s25, s25, 0
	s_mov_b32 m0, s40
	v_lshl_add_u64 v[208:209], s[24:25], 0, v[132:133]
	ds_read_b128 v[180:183], v159 offset:32768
	ds_read_b128 v[184:187], v159 offset:33792
	ds_read_b128 v[188:191], v159 offset:34816
	ds_read_b128 v[192:195], v159 offset:35840
	ds_read_b128 v[196:199], v159 offset:36864
	ds_read_b128 v[200:203], v159 offset:37888
	ds_read_b128 v[212:215], v159 offset:38912
	ds_read_b128 v[220:223], v159 offset:39936
	global_load_lds_dwordx4 v[208:209], off
	v_lshl_add_u64 v[208:209], s[24:25], 0, v[130:131]
	s_mov_b32 m0, s41
	s_nop 0
	global_load_lds_dwordx4 v[208:209], off
	s_waitcnt vmcnt(8)
	s_waitcnt lgkmcnt(0)
	s_setprio 0
	s_barrier
	s_waitcnt lgkmcnt(0)
	v_mfma_f32_16x16x32_bf16 v[124:127], v[138:141], v[180:183], v[124:127]
	v_mfma_f32_16x16x32_bf16 v[120:123], v[154:157], v[180:183], v[120:123]
	v_mfma_f32_16x16x32_bf16 v[108:111], v[138:141], v[188:191], v[108:111]
	v_mfma_f32_16x16x32_bf16 v[104:107], v[154:157], v[188:191], v[104:107]
	v_mfma_f32_16x16x32_bf16 v[92:95], v[138:141], v[196:199], v[92:95]
	v_mfma_f32_16x16x32_bf16 v[88:91], v[154:157], v[196:199], v[88:91]
	v_mfma_f32_16x16x32_bf16 v[76:79], v[138:141], v[212:215], v[76:79]
	v_mfma_f32_16x16x32_bf16 v[72:75], v[154:157], v[212:215], v[72:75]
	v_mfma_f32_16x16x32_bf16 v[124:127], v[142:145], v[184:187], v[124:127]
	v_mfma_f32_16x16x32_bf16 v[120:123], v[160:163], v[184:187], v[120:123]
	v_mfma_f32_16x16x32_bf16 v[108:111], v[142:145], v[192:195], v[108:111]
	v_mfma_f32_16x16x32_bf16 v[104:107], v[160:163], v[192:195], v[104:107]
	v_mfma_f32_16x16x32_bf16 v[92:95], v[142:145], v[200:203], v[92:95]
	v_mfma_f32_16x16x32_bf16 v[88:91], v[160:163], v[200:203], v[88:91]
	v_mfma_f32_16x16x32_bf16 v[76:79], v[142:145], v[220:223], v[76:79]
	v_mfma_f32_16x16x32_bf16 v[72:75], v[160:163], v[220:223], v[72:75]
	v_mfma_f32_16x16x32_bf16 v[116:119], v[164:167], v[180:183], v[116:119]
	v_mfma_f32_16x16x32_bf16 v[112:115], v[172:175], v[180:183], v[112:115]
	v_mfma_f32_16x16x32_bf16 v[100:103], v[164:167], v[188:191], v[100:103]
	v_mfma_f32_16x16x32_bf16 v[96:99], v[172:175], v[188:191], v[96:99]
	v_mfma_f32_16x16x32_bf16 v[84:87], v[164:167], v[196:199], v[84:87]
	v_mfma_f32_16x16x32_bf16 v[80:83], v[172:175], v[196:199], v[80:83]
	v_mfma_f32_16x16x32_bf16 v[68:71], v[164:167], v[212:215], v[68:71]
	v_mfma_f32_16x16x32_bf16 v[64:67], v[172:175], v[212:215], v[64:67]
	v_mfma_f32_16x16x32_bf16 v[116:119], v[168:171], v[184:187], v[116:119]
	v_mfma_f32_16x16x32_bf16 v[112:115], v[176:179], v[184:187], v[112:115]
	v_mfma_f32_16x16x32_bf16 v[100:103], v[168:171], v[192:195], v[100:103]
	v_mfma_f32_16x16x32_bf16 v[96:99], v[176:179], v[192:195], v[96:99]
	v_mfma_f32_16x16x32_bf16 v[84:87], v[168:171], v[200:203], v[84:87]
	v_mfma_f32_16x16x32_bf16 v[80:83], v[176:179], v[200:203], v[80:83]
	v_mfma_f32_16x16x32_bf16 v[68:71], v[168:171], v[220:223], v[68:71]
	v_mfma_f32_16x16x32_bf16 v[64:67], v[176:179], v[220:223], v[64:67]
	s_barrier
	s_setprio 1
	s_add_i32 s24, s54, s37
	v_lshl_add_u64 v[146:147], v[146:147], 0, s[28:29]
	s_mov_b32 m0, s24
	ds_read_b128 v[180:183], v159 offset:49152
	ds_read_b128 v[184:187], v159 offset:50176
	ds_read_b128 v[188:191], v159 offset:51200
	ds_read_b128 v[192:195], v159 offset:52224
	ds_read_b128 v[196:199], v159 offset:53248
	ds_read_b128 v[200:203], v159 offset:54272
	ds_read_b128 v[212:215], v159 offset:55296
	ds_read_b128 v[220:223], v159 offset:56320
	global_load_lds_dwordx4 v[146:147], off
	s_add_i32 m0, s24, 0x2000
	s_add_u32 s22, s22, 0x20080
	v_lshl_add_u64 v[146:147], v[150:151], 0, s[28:29]
	s_addc_u32 s23, s23, 0
	s_add_i32 s24, s55, s37
	global_load_lds_dwordx4 v[146:147], off
	v_lshl_add_u64 v[146:147], s[22:23], 0, v[148:149]
	s_mov_b32 m0, s24
	s_nop 0
	global_load_lds_dwordx4 v[146:147], off
	v_lshl_add_u64 v[146:147], s[22:23], 0, v[128:129]
	s_add_i32 m0, s24, 0x2000
	s_nop 0
	global_load_lds_dwordx4 v[146:147], off
	v_lshl_add_u64 v[146:147], v[152:153], 0, s[28:29]
	s_mov_b32 m0, s45
	s_nop 0
	global_load_lds_dwordx4 v[146:147], off
	v_lshl_add_u64 v[146:147], v[204:205], 0, s[28:29]
	s_mov_b32 m0, s46
	s_nop 0
	global_load_lds_dwordx4 v[146:147], off
	s_waitcnt vmcnt(8)
	s_waitcnt lgkmcnt(0)
	s_setprio 0
	s_barrier
	s_waitcnt lgkmcnt(0)
	v_mfma_f32_16x16x32_bf16 v[60:63], v[138:141], v[180:183], v[60:63]
	v_mfma_f32_16x16x32_bf16 v[56:59], v[154:157], v[180:183], v[56:59]
	v_mfma_f32_16x16x32_bf16 v[44:47], v[138:141], v[188:191], v[44:47]
	v_mfma_f32_16x16x32_bf16 v[40:43], v[154:157], v[188:191], v[40:43]
	v_mfma_f32_16x16x32_bf16 v[28:31], v[138:141], v[196:199], v[28:31]
	v_mfma_f32_16x16x32_bf16 v[24:27], v[154:157], v[196:199], v[24:27]
	v_mfma_f32_16x16x32_bf16 v[12:15], v[138:141], v[212:215], v[12:15]
	v_mfma_f32_16x16x32_bf16 v[8:11], v[154:157], v[212:215], v[8:11]
	v_mfma_f32_16x16x32_bf16 v[60:63], v[142:145], v[184:187], v[60:63]
	v_mfma_f32_16x16x32_bf16 v[56:59], v[160:163], v[184:187], v[56:59]
	v_mfma_f32_16x16x32_bf16 v[44:47], v[142:145], v[192:195], v[44:47]
	v_mfma_f32_16x16x32_bf16 v[40:43], v[160:163], v[192:195], v[40:43]
	v_mfma_f32_16x16x32_bf16 v[28:31], v[142:145], v[200:203], v[28:31]
	v_mfma_f32_16x16x32_bf16 v[24:27], v[160:163], v[200:203], v[24:27]
	v_mfma_f32_16x16x32_bf16 v[12:15], v[142:145], v[220:223], v[12:15]
	v_mfma_f32_16x16x32_bf16 v[8:11], v[160:163], v[220:223], v[8:11]
	v_mfma_f32_16x16x32_bf16 v[52:55], v[164:167], v[180:183], v[52:55]
	v_mfma_f32_16x16x32_bf16 v[48:51], v[172:175], v[180:183], v[48:51]
	v_mfma_f32_16x16x32_bf16 v[36:39], v[164:167], v[188:191], v[36:39]
	v_mfma_f32_16x16x32_bf16 v[32:35], v[172:175], v[188:191], v[32:35]
	v_mfma_f32_16x16x32_bf16 v[20:23], v[164:167], v[196:199], v[20:23]
	v_mfma_f32_16x16x32_bf16 v[16:19], v[172:175], v[196:199], v[16:19]
	v_mfma_f32_16x16x32_bf16 v[4:7], v[164:167], v[212:215], v[4:7]
	v_mfma_f32_16x16x32_bf16 v[0:3], v[172:175], v[212:215], v[0:3]
	v_mfma_f32_16x16x32_bf16 v[52:55], v[168:171], v[184:187], v[52:55]
	v_mfma_f32_16x16x32_bf16 v[48:51], v[176:179], v[184:187], v[48:51]
	v_mfma_f32_16x16x32_bf16 v[36:39], v[168:171], v[192:195], v[36:39]
	v_mfma_f32_16x16x32_bf16 v[32:35], v[176:179], v[192:195], v[32:35]
	v_mfma_f32_16x16x32_bf16 v[20:23], v[168:171], v[200:203], v[20:23]
	v_mfma_f32_16x16x32_bf16 v[16:19], v[176:179], v[200:203], v[16:19]
	v_mfma_f32_16x16x32_bf16 v[4:7], v[168:171], v[220:223], v[4:7]
	v_mfma_f32_16x16x32_bf16 v[0:3], v[176:179], v[220:223], v[0:3]
	s_barrier
	s_setprio 1
	s_add_i32 s53, s53, 2
	s_add_u32 s8, s8, 0x100
	s_addc_u32 s9, s9, 0
	s_add_u32 s51, s51, 0x100
	s_addc_u32 s52, s52, 0
	s_cmp_gt_u32 s53, 5
	s_cbranch_scc0 .LBB0_1335
	s_setprio 0
	s_and_b64 vcc, exec, s[12:13]
	s_cbranch_vccz .LBB0_1338
	s_barrier

.LBB0_1438:
	s_add_u32 s20, s18, 0xfffc0080
	s_addc_u32 s21, s19, -1
	s_add_i32 s49, 0, 0x10000
	s_cmp_eq_u32 s48, 12
	s_cselect_b32 s23, s13, s21
	s_cselect_b32 s22, s44, s20
	v_add_u32_e32 v142, s49, v144
	s_cselect_b32 s21, s11, s47
	s_cselect_b32 s20, s45, s46
	s_add_i32 s52, 0, 0x14000
	ds_read_b128 v[138:141], v142
	ds_read_b128 v[154:157], v142 offset:1024
	ds_read_b128 v[158:161], v142 offset:2048
	ds_read_b128 v[162:165], v142 offset:3072
	v_add_u32_e32 v142, s52, v144
	ds_read_b128 v[166:169], v142
	ds_read_b128 v[170:173], v142 offset:1024
	ds_read_b128 v[174:177], v142 offset:2048
	ds_read_b128 v[178:181], v142 offset:3072
	v_lshl_add_u64 v[142:143], s[18:19], 0, v[134:135]
	s_add_i32 m0, s31, 0xc000
	ds_read_b128 v[182:185], v145
	ds_read_b128 v[186:189], v145 offset:1024
	ds_read_b128 v[190:193], v145 offset:2048
	ds_read_b128 v[194:197], v145 offset:3072
	ds_read_b128 v[198:201], v145 offset:4096
	ds_read_b128 v[202:205], v145 offset:5120
	ds_read_b128 v[212:215], v145 offset:6144
	ds_read_b128 v[220:223], v145 offset:7168
	global_load_lds_dwordx4 v[142:143], off
	v_lshl_add_u64 v[142:143], s[18:19], 0, v[136:137]
	s_add_i32 m0, s31, 0xe000
	s_nop 0
	global_load_lds_dwordx4 v[142:143], off
	s_waitcnt vmcnt(8)
	s_waitcnt lgkmcnt(0)
	s_setprio 0
	s_barrier
	s_waitcnt lgkmcnt(0)
	v_mfma_f32_16x16x32_bf16 v[124:127], v[138:141], v[182:185], v[124:127]
	v_mfma_f32_16x16x32_bf16 v[120:123], v[158:161], v[182:185], v[120:123]
	v_mfma_f32_16x16x32_bf16 v[108:111], v[138:141], v[190:193], v[108:111]
	v_mfma_f32_16x16x32_bf16 v[104:107], v[158:161], v[190:193], v[104:107]
	v_mfma_f32_16x16x32_bf16 v[92:95], v[138:141], v[198:201], v[92:95]
	v_mfma_f32_16x16x32_bf16 v[88:91], v[158:161], v[198:201], v[88:91]
	v_mfma_f32_16x16x32_bf16 v[76:79], v[138:141], v[212:215], v[76:79]
	v_mfma_f32_16x16x32_bf16 v[72:75], v[158:161], v[212:215], v[72:75]
	v_mfma_f32_16x16x32_bf16 v[124:127], v[154:157], v[186:189], v[124:127]
	v_mfma_f32_16x16x32_bf16 v[120:123], v[162:165], v[186:189], v[120:123]
	v_mfma_f32_16x16x32_bf16 v[108:111], v[154:157], v[194:197], v[108:111]
	v_mfma_f32_16x16x32_bf16 v[104:107], v[162:165], v[194:197], v[104:107]
	v_mfma_f32_16x16x32_bf16 v[92:95], v[154:157], v[202:205], v[92:95]
	v_mfma_f32_16x16x32_bf16 v[88:91], v[162:165], v[202:205], v[88:91]
	v_mfma_f32_16x16x32_bf16 v[76:79], v[154:157], v[220:223], v[76:79]
	v_mfma_f32_16x16x32_bf16 v[72:75], v[162:165], v[220:223], v[72:75]
	v_mfma_f32_16x16x32_bf16 v[116:119], v[166:169], v[182:185], v[116:119]
	v_mfma_f32_16x16x32_bf16 v[112:115], v[174:177], v[182:185], v[112:115]
	v_mfma_f32_16x16x32_bf16 v[100:103], v[166:169], v[190:193], v[100:103]
	v_mfma_f32_16x16x32_bf16 v[96:99], v[174:177], v[190:193], v[96:99]
	v_mfma_f32_16x16x32_bf16 v[84:87], v[166:169], v[198:201], v[84:87]
	v_mfma_f32_16x16x32_bf16 v[80:83], v[174:177], v[198:201], v[80:83]
	v_mfma_f32_16x16x32_bf16 v[68:71], v[166:169], v[212:215], v[68:71]
	v_mfma_f32_16x16x32_bf16 v[64:67], v[174:177], v[212:215], v[64:67]
	v_mfma_f32_16x16x32_bf16 v[116:119], v[170:173], v[186:189], v[116:119]
	v_mfma_f32_16x16x32_bf16 v[112:115], v[178:181], v[186:189], v[112:115]
	v_mfma_f32_16x16x32_bf16 v[100:103], v[170:173], v[194:197], v[100:103]
	v_mfma_f32_16x16x32_bf16 v[96:99], v[178:181], v[194:197], v[96:99]
	v_mfma_f32_16x16x32_bf16 v[84:87], v[170:173], v[202:205], v[84:87]
	v_mfma_f32_16x16x32_bf16 v[80:83], v[178:181], v[202:205], v[80:83]
	v_mfma_f32_16x16x32_bf16 v[68:71], v[170:173], v[220:223], v[68:71]
	v_mfma_f32_16x16x32_bf16 v[64:67], v[178:181], v[220:223], v[64:67]
	s_barrier
	s_setprio 1
	s_add_i32 s49, s49, s30
	v_lshl_add_u64 v[142:143], s[20:21], 0, v[148:149]
	s_mov_b32 m0, s49
	ds_read_b128 v[182:185], v145 offset:16384
	ds_read_b128 v[186:189], v145 offset:17408
	ds_read_b128 v[190:193], v145 offset:18432
	ds_read_b128 v[194:197], v145 offset:19456
	ds_read_b128 v[198:201], v145 offset:20480
	ds_read_b128 v[202:205], v145 offset:21504
	ds_read_b128 v[212:215], v145 offset:22528
	ds_read_b128 v[220:223], v145 offset:23552
	global_load_lds_dwordx4 v[142:143], off
	s_add_i32 m0, s49, 0x2000
	s_add_u32 s50, s20, 0x40000
	v_lshl_add_u64 v[146:147], s[20:21], 0, v[128:129]
	s_addc_u32 s51, s21, 0
	s_add_i32 s49, s52, s30
	global_load_lds_dwordx4 v[146:147], off
	v_lshl_add_u64 v[150:151], s[50:51], 0, v[148:149]
	s_mov_b32 m0, s49
	v_lshl_add_u64 v[152:153], s[22:23], 0, v[130:131]
	global_load_lds_dwordx4 v[150:151], off
	v_lshl_add_u64 v[150:151], s[50:51], 0, v[128:129]
	s_add_i32 m0, s49, 0x2000
	s_nop 0
	global_load_lds_dwordx4 v[150:151], off
	v_lshl_add_u64 v[150:151], s[22:23], 0, v[132:133]
	s_mov_b32 m0, s31
	s_nop 0
	global_load_lds_dwordx4 v[150:151], off
	s_mov_b32 m0, s33
	s_nop 0
	global_load_lds_dwordx4 v[152:153], off
	s_waitcnt vmcnt(8)
	s_waitcnt lgkmcnt(0)
	s_setprio 0
	s_barrier
	s_waitcnt lgkmcnt(0)
	v_mfma_f32_16x16x32_bf16 v[60:63], v[138:141], v[182:185], v[60:63]
	v_mfma_f32_16x16x32_bf16 v[56:59], v[158:161], v[182:185], v[56:59]
	v_mfma_f32_16x16x32_bf16 v[44:47], v[138:141], v[190:193], v[44:47]
	v_mfma_f32_16x16x32_bf16 v[40:43], v[158:161], v[190:193], v[40:43]
	v_mfma_f32_16x16x32_bf16 v[28:31], v[138:141], v[198:201], v[28:31]
	v_mfma_f32_16x16x32_bf16 v[24:27], v[158:161], v[198:201], v[24:27]
	v_mfma_f32_16x16x32_bf16 v[12:15], v[138:141], v[212:215], v[12:15]
	v_mfma_f32_16x16x32_bf16 v[8:11], v[158:161], v[212:215], v[8:11]
	v_mfma_f32_16x16x32_bf16 v[60:63], v[154:157], v[186:189], v[60:63]
	v_mfma_f32_16x16x32_bf16 v[56:59], v[162:165], v[186:189], v[56:59]
	v_mfma_f32_16x16x32_bf16 v[44:47], v[154:157], v[194:197], v[44:47]
	v_mfma_f32_16x16x32_bf16 v[40:43], v[162:165], v[194:197], v[40:43]
	v_mfma_f32_16x16x32_bf16 v[28:31], v[154:157], v[202:205], v[28:31]
	v_mfma_f32_16x16x32_bf16 v[24:27], v[162:165], v[202:205], v[24:27]
	v_mfma_f32_16x16x32_bf16 v[12:15], v[154:157], v[220:223], v[12:15]
	v_mfma_f32_16x16x32_bf16 v[8:11], v[162:165], v[220:223], v[8:11]
	v_mfma_f32_16x16x32_bf16 v[52:55], v[166:169], v[182:185], v[52:55]
	v_mfma_f32_16x16x32_bf16 v[48:51], v[174:177], v[182:185], v[48:51]
	v_mfma_f32_16x16x32_bf16 v[36:39], v[166:169], v[190:193], v[36:39]
	v_mfma_f32_16x16x32_bf16 v[32:35], v[174:177], v[190:193], v[32:35]
	v_mfma_f32_16x16x32_bf16 v[20:23], v[166:169], v[198:201], v[20:23]
	v_mfma_f32_16x16x32_bf16 v[16:19], v[174:177], v[198:201], v[16:19]
	v_mfma_f32_16x16x32_bf16 v[4:7], v[166:169], v[212:215], v[4:7]
	v_mfma_f32_16x16x32_bf16 v[0:3], v[174:177], v[212:215], v[0:3]
	v_mfma_f32_16x16x32_bf16 v[52:55], v[170:173], v[186:189], v[52:55]
	v_mfma_f32_16x16x32_bf16 v[48:51], v[178:181], v[186:189], v[48:51]
	v_mfma_f32_16x16x32_bf16 v[36:39], v[170:173], v[194:197], v[36:39]
	v_mfma_f32_16x16x32_bf16 v[32:35], v[178:181], v[194:197], v[32:35]
	v_mfma_f32_16x16x32_bf16 v[20:23], v[170:173], v[202:205], v[20:23]
	v_mfma_f32_16x16x32_bf16 v[16:19], v[178:181], v[202:205], v[16:19]
	v_mfma_f32_16x16x32_bf16 v[4:7], v[170:173], v[220:223], v[4:7]
	v_mfma_f32_16x16x32_bf16 v[0:3], v[178:181], v[220:223], v[0:3]
	s_barrier
	s_setprio 1
	s_add_i32 s49, 0, 0x18000
	s_add_i32 s50, 0, 0x1c000
	v_add_u32_e32 v162, s49, v144
	v_add_u32_e32 v178, s50, v144
	ds_read_b128 v[138:141], v162
	ds_read_b128 v[154:157], v162 offset:1024
	ds_read_b128 v[158:161], v162 offset:2048
	ds_read_b128 v[162:165], v162 offset:3072
	ds_read_b128 v[166:169], v178
	ds_read_b128 v[170:173], v178 offset:1024
	ds_read_b128 v[174:177], v178 offset:2048
	ds_read_b128 v[178:181], v178 offset:3072
	s_add_u32 s22, s22, 0x40000
	s_addc_u32 s23, s23, 0
	s_mov_b32 m0, s34
	v_lshl_add_u64 v[208:209], s[22:23], 0, v[132:133]
	ds_read_b128 v[182:185], v145 offset:32768
	ds_read_b128 v[186:189], v145 offset:33792
	ds_read_b128 v[190:193], v145 offset:34816
	ds_read_b128 v[194:197], v145 offset:35840
	ds_read_b128 v[198:201], v145 offset:36864
	ds_read_b128 v[202:205], v145 offset:37888
	ds_read_b128 v[212:215], v145 offset:38912
	ds_read_b128 v[220:223], v145 offset:39936
	global_load_lds_dwordx4 v[208:209], off
	v_lshl_add_u64 v[208:209], s[22:23], 0, v[130:131]
	s_mov_b32 m0, s35
	s_nop 0
	global_load_lds_dwordx4 v[208:209], off
	s_waitcnt vmcnt(8)
	s_waitcnt lgkmcnt(0)
	s_setprio 0
	s_barrier
	s_waitcnt lgkmcnt(0)
	v_mfma_f32_16x16x32_bf16 v[124:127], v[138:141], v[182:185], v[124:127]
	v_mfma_f32_16x16x32_bf16 v[120:123], v[158:161], v[182:185], v[120:123]
	v_mfma_f32_16x16x32_bf16 v[108:111], v[138:141], v[190:193], v[108:111]
	v_mfma_f32_16x16x32_bf16 v[104:107], v[158:161], v[190:193], v[104:107]
	v_mfma_f32_16x16x32_bf16 v[92:95], v[138:141], v[198:201], v[92:95]
	v_mfma_f32_16x16x32_bf16 v[88:91], v[158:161], v[198:201], v[88:91]
	v_mfma_f32_16x16x32_bf16 v[76:79], v[138:141], v[212:215], v[76:79]
	v_mfma_f32_16x16x32_bf16 v[72:75], v[158:161], v[212:215], v[72:75]
	v_mfma_f32_16x16x32_bf16 v[124:127], v[154:157], v[186:189], v[124:127]
	v_mfma_f32_16x16x32_bf16 v[120:123], v[162:165], v[186:189], v[120:123]
	v_mfma_f32_16x16x32_bf16 v[108:111], v[154:157], v[194:197], v[108:111]
	v_mfma_f32_16x16x32_bf16 v[104:107], v[162:165], v[194:197], v[104:107]
	v_mfma_f32_16x16x32_bf16 v[92:95], v[154:157], v[202:205], v[92:95]
	v_mfma_f32_16x16x32_bf16 v[88:91], v[162:165], v[202:205], v[88:91]
	v_mfma_f32_16x16x32_bf16 v[76:79], v[154:157], v[220:223], v[76:79]
	v_mfma_f32_16x16x32_bf16 v[72:75], v[162:165], v[220:223], v[72:75]
	v_mfma_f32_16x16x32_bf16 v[116:119], v[166:169], v[182:185], v[116:119]
	v_mfma_f32_16x16x32_bf16 v[112:115], v[174:177], v[182:185], v[112:115]
	v_mfma_f32_16x16x32_bf16 v[100:103], v[166:169], v[190:193], v[100:103]
	v_mfma_f32_16x16x32_bf16 v[96:99], v[174:177], v[190:193], v[96:99]
	v_mfma_f32_16x16x32_bf16 v[84:87], v[166:169], v[198:201], v[84:87]
	v_mfma_f32_16x16x32_bf16 v[80:83], v[174:177], v[198:201], v[80:83]
	v_mfma_f32_16x16x32_bf16 v[68:71], v[166:169], v[212:215], v[68:71]
	v_mfma_f32_16x16x32_bf16 v[64:67], v[174:177], v[212:215], v[64:67]
	v_mfma_f32_16x16x32_bf16 v[116:119], v[170:173], v[186:189], v[116:119]
	v_mfma_f32_16x16x32_bf16 v[112:115], v[178:181], v[186:189], v[112:115]
	v_mfma_f32_16x16x32_bf16 v[100:103], v[170:173], v[194:197], v[100:103]
	v_mfma_f32_16x16x32_bf16 v[96:99], v[178:181], v[194:197], v[96:99]
	v_mfma_f32_16x16x32_bf16 v[84:87], v[170:173], v[202:205], v[84:87]
	v_mfma_f32_16x16x32_bf16 v[80:83], v[178:181], v[202:205], v[80:83]
	v_mfma_f32_16x16x32_bf16 v[68:71], v[170:173], v[220:223], v[68:71]
	v_mfma_f32_16x16x32_bf16 v[64:67], v[178:181], v[220:223], v[64:67]
	s_barrier
	s_setprio 1
	s_add_i32 s22, s49, s30
	v_lshl_add_u64 v[142:143], v[142:143], 0, s[28:29]
	s_mov_b32 m0, s22
	ds_read_b128 v[182:185], v145 offset:49152
	ds_read_b128 v[186:189], v145 offset:50176
	ds_read_b128 v[190:193], v145 offset:51200
	ds_read_b128 v[194:197], v145 offset:52224
	ds_read_b128 v[198:201], v145 offset:53248
	ds_read_b128 v[202:205], v145 offset:54272
	ds_read_b128 v[212:215], v145 offset:55296
	ds_read_b128 v[220:223], v145 offset:56320
	global_load_lds_dwordx4 v[142:143], off
	s_add_i32 m0, s22, 0x2000
	s_add_u32 s20, s20, 0x40080
	v_lshl_add_u64 v[142:143], v[146:147], 0, s[28:29]
	s_addc_u32 s21, s21, 0
	s_add_i32 s22, s50, s30
	global_load_lds_dwordx4 v[142:143], off
	v_lshl_add_u64 v[142:143], s[20:21], 0, v[148:149]
	s_mov_b32 m0, s22
	s_nop 0
	global_load_lds_dwordx4 v[142:143], off
	v_lshl_add_u64 v[142:143], s[20:21], 0, v[128:129]
	s_add_i32 m0, s22, 0x2000
	s_nop 0
	global_load_lds_dwordx4 v[142:143], off
	v_lshl_add_u64 v[142:143], v[150:151], 0, s[28:29]
	s_mov_b32 m0, s39
	s_nop 0
	global_load_lds_dwordx4 v[142:143], off
	v_lshl_add_u64 v[142:143], v[152:153], 0, s[28:29]
	s_mov_b32 m0, s40
	s_nop 0
	global_load_lds_dwordx4 v[142:143], off
	s_waitcnt vmcnt(8)
	s_waitcnt lgkmcnt(0)
	s_setprio 0
	s_barrier
	s_waitcnt lgkmcnt(0)
	v_mfma_f32_16x16x32_bf16 v[60:63], v[138:141], v[182:185], v[60:63]
	v_mfma_f32_16x16x32_bf16 v[56:59], v[158:161], v[182:185], v[56:59]
	v_mfma_f32_16x16x32_bf16 v[44:47], v[138:141], v[190:193], v[44:47]
	v_mfma_f32_16x16x32_bf16 v[40:43], v[158:161], v[190:193], v[40:43]
	v_mfma_f32_16x16x32_bf16 v[28:31], v[138:141], v[198:201], v[28:31]
	v_mfma_f32_16x16x32_bf16 v[24:27], v[158:161], v[198:201], v[24:27]
	v_mfma_f32_16x16x32_bf16 v[12:15], v[138:141], v[212:215], v[12:15]
	v_mfma_f32_16x16x32_bf16 v[8:11], v[158:161], v[212:215], v[8:11]
	v_mfma_f32_16x16x32_bf16 v[60:63], v[154:157], v[186:189], v[60:63]
	v_mfma_f32_16x16x32_bf16 v[56:59], v[162:165], v[186:189], v[56:59]
	v_mfma_f32_16x16x32_bf16 v[44:47], v[154:157], v[194:197], v[44:47]
	v_mfma_f32_16x16x32_bf16 v[40:43], v[162:165], v[194:197], v[40:43]
	v_mfma_f32_16x16x32_bf16 v[28:31], v[154:157], v[202:205], v[28:31]
	v_mfma_f32_16x16x32_bf16 v[24:27], v[162:165], v[202:205], v[24:27]
	v_mfma_f32_16x16x32_bf16 v[12:15], v[154:157], v[220:223], v[12:15]
	v_mfma_f32_16x16x32_bf16 v[8:11], v[162:165], v[220:223], v[8:11]
	v_mfma_f32_16x16x32_bf16 v[52:55], v[166:169], v[182:185], v[52:55]
	v_mfma_f32_16x16x32_bf16 v[48:51], v[174:177], v[182:185], v[48:51]
	v_mfma_f32_16x16x32_bf16 v[36:39], v[166:169], v[190:193], v[36:39]
	v_mfma_f32_16x16x32_bf16 v[32:35], v[174:177], v[190:193], v[32:35]
	v_mfma_f32_16x16x32_bf16 v[20:23], v[166:169], v[198:201], v[20:23]
	v_mfma_f32_16x16x32_bf16 v[16:19], v[174:177], v[198:201], v[16:19]
	v_mfma_f32_16x16x32_bf16 v[4:7], v[166:169], v[212:215], v[4:7]
	v_mfma_f32_16x16x32_bf16 v[0:3], v[174:177], v[212:215], v[0:3]
	v_mfma_f32_16x16x32_bf16 v[52:55], v[170:173], v[186:189], v[52:55]
	v_mfma_f32_16x16x32_bf16 v[48:51], v[178:181], v[186:189], v[48:51]
	v_mfma_f32_16x16x32_bf16 v[36:39], v[170:173], v[194:197], v[36:39]
	v_mfma_f32_16x16x32_bf16 v[32:35], v[178:181], v[194:197], v[32:35]
	v_mfma_f32_16x16x32_bf16 v[20:23], v[170:173], v[202:205], v[20:23]
	v_mfma_f32_16x16x32_bf16 v[16:19], v[178:181], v[202:205], v[16:19]
	v_mfma_f32_16x16x32_bf16 v[4:7], v[170:173], v[220:223], v[4:7]
	v_mfma_f32_16x16x32_bf16 v[0:3], v[178:181], v[220:223], v[0:3]
	s_barrier
	s_setprio 1
	s_add_i32 s48, s48, 2
	s_add_u32 s18, s18, 0x100
	s_addc_u32 s19, s19, 0
	s_add_u32 s46, s46, 0x100
	s_addc_u32 s47, s47, 0
	s_cmp_gt_u32 s48, 13
	s_cbranch_scc0 .LBB0_1438
	s_setprio 0
	s_and_b64 vcc, exec, s[8:9]
	s_cbranch_vccz .LBB0_1441
	s_barrier
